# adds: attention K/V LDS staging overlapped with PV MFMAs (V prefetch at tile top), mini-GEMM loops: unconditional ring prefetch + counted vmcnt + pipelined LDS fragment reads
# speedup vs baseline: 1.0076x; 1.0076x over previous
; DEV uint32_t pk2(float lo, float hi) { f32x2 v; v[0] = lo; v[1] = hi; bf16v2 b = __builtin_convertvector(v, bf16v2); return __builtin_bit_cast(uint32_t, b); }
; DEV float rscale_of(const float* ssq, int m) {
;   const f32x4 a = *(const f32x4*)(ssq + (size_t)m * NPART), b = *(const f32x4*)(ssq + (size_t)m * NPART + 4);
;   const float s = (a[0] + a[1]) + (a[2] + a[3]) + (b[0] + b[1]) + (b[2] + b[3]);
;   return rsqrtf(s * (1.f / DM) + EPS);
; }
; template <int EPI>
; DEV void gemm_mini(CParams& p, int layer, const bf16_t* __restrict__ A, int lda, const bf16_t* __restrict__ Bt, int K, int n0, char* lds, const int swave) {
;     ...
;     const float rs = rscale_of(ssq, mc);
;     bf16_t* urow = (bf16_t*)(ws + W_U) + (size_t)mc * DFF;
; #pragma unroll
;     for (int j = 0; j < 4; ++j)
; #pragma unroll
;       for (int g = 0; g < 4; ++g) {
;         const int n = n0 + j * 32 + 8 * g + 4 * hh;
;         float v0 = fmaxf(acc[j][4 * g] * rs, 0.f), v1 = fmaxf(acc[j][4 * g + 1] * rs, 0.f), v2 = fmaxf(acc[j][4 * g + 2] * rs, 0.f), v3 = fmaxf(acc[j][4 * g + 3] * rs, 0.f);
;         u32x2 pk; pk[0] = pk2(v0 * v0, v1 * v1); pk[1] = pk2(v2 * v2, v3 * v3);
;         *(u32x2*)(urow + n) = pk;
;       }
.LBB0_139:
	s_waitcnt vmcnt(0)
	v_or_b32_e32 v240, s19, v68
	v_lshlrev_b64 v[64:65], 5, v[240:241]
	v_lshl_add_u64 v[64:65], s[4:5], 0, v[64:65]
	global_load_dwordx4 v[68:71], v[64:65], off
	global_load_dwordx4 v[72:75], v[64:65], off offset:16
	v_lshl_or_b32 v64, v66, 2, s92
	v_lshlrev_b64 v[66:67], 13, v[240:241]
	v_lshl_add_u64 v[66:67], s[6:7], 0, v[66:67]
	v_accvgpr_read_b32 v63, a15
	v_accvgpr_read_b32 v16, a32
	v_accvgpr_read_b32 v0, a48
	v_accvgpr_read_b32 v51, a3
	v_accvgpr_read_b32 v50, a2
	v_accvgpr_read_b32 v49, a1
	v_accvgpr_read_b32 v48, a0
	v_accvgpr_read_b32 v47, a31
	v_accvgpr_read_b32 v17, a33
	v_accvgpr_read_b32 v18, a34
	v_accvgpr_read_b32 v19, a35
	v_accvgpr_read_b32 v1, a49
	v_accvgpr_read_b32 v2, a50
	v_accvgpr_read_b32 v3, a51
	v_accvgpr_read_b32 v62, a14
	v_accvgpr_read_b32 v61, a13
	v_accvgpr_read_b32 v60, a12
	v_accvgpr_read_b32 v59, a11
	v_accvgpr_read_b32 v58, a10
	v_accvgpr_read_b32 v57, a9
	v_accvgpr_read_b32 v56, a8
	v_accvgpr_read_b32 v55, a7
	v_accvgpr_read_b32 v54, a6
	v_accvgpr_read_b32 v53, a5
	v_accvgpr_read_b32 v52, a4
	v_accvgpr_read_b32 v35, a19
	v_accvgpr_read_b32 v34, a18
	v_accvgpr_read_b32 v33, a17
	v_accvgpr_read_b32 v32, a16
	v_accvgpr_read_b32 v39, a23
	v_accvgpr_read_b32 v38, a22
	v_accvgpr_read_b32 v37, a21
	v_accvgpr_read_b32 v36, a20
	v_accvgpr_read_b32 v20, a36
	v_accvgpr_read_b32 v21, a37
	v_accvgpr_read_b32 v22, a38
	v_accvgpr_read_b32 v23, a39
	v_accvgpr_read_b32 v4, a52
	v_accvgpr_read_b32 v5, a53
	v_accvgpr_read_b32 v6, a54
	v_accvgpr_read_b32 v7, a55
	v_accvgpr_read_b32 v43, a27
	v_accvgpr_read_b32 v42, a26
	v_accvgpr_read_b32 v41, a25
	v_accvgpr_read_b32 v40, a24
	v_accvgpr_read_b32 v24, a40
	v_accvgpr_read_b32 v25, a41
	v_accvgpr_read_b32 v26, a42
	v_accvgpr_read_b32 v27, a43
	v_accvgpr_read_b32 v8, a56
	v_accvgpr_read_b32 v9, a57
	v_accvgpr_read_b32 v10, a58
	v_accvgpr_read_b32 v11, a59
	v_accvgpr_read_b32 v46, a30
	v_accvgpr_read_b32 v45, a29
	v_accvgpr_read_b32 v44, a28
	v_accvgpr_read_b32 v28, a44
	v_accvgpr_read_b32 v29, a45
	v_accvgpr_read_b32 v30, a46
	v_accvgpr_read_b32 v31, a47
	v_accvgpr_read_b32 v12, a60
	v_accvgpr_read_b32 v13, a61
	v_accvgpr_read_b32 v14, a62
	v_accvgpr_read_b32 v15, a63
	s_add_i32 s28, s28, s11
	s_add_i32 s90, s90, s44
	s_cmp_lt_i32 s28, 32
	s_waitcnt vmcnt(1)
	v_mov_b32_e32 v76, v69
	v_mov_b32_e32 v77, v70
	v_mov_b32_e32 v69, v71
	s_waitcnt vmcnt(0)
	v_mov_b32_e32 v70, v74
	v_mov_b32_e32 v71, v72
	v_mov_b32_e32 v72, v75
	v_pk_add_f32 v[68:69], v[76:77], v[68:69]
	v_pk_add_f32 v[70:71], v[70:71], v[72:73]
	v_add_f32_e32 v65, v68, v69
	v_add_f32_e32 v65, v65, v71
	v_add_f32_e32 v65, v70, v65
	v_fmamk_f32 v65, v65, 0x3a800000, v242
	v_mul_f32_e32 v68, 0x4b800000, v65
	v_cmp_gt_f32_e32 vcc, s25, v65
	s_nop 1
	v_cndmask_b32_e32 v65, v65, v68, vcc
	v_rsq_f32_e32 v68, v65
	v_ashrrev_i32_e32 v65, 31, v64
	v_lshl_add_u64 v[64:65], v[64:65], 1, v[66:67]
	v_mul_f32_e32 v66, 0x45800000, v68
	v_cndmask_b32_e32 v66, v68, v66, vcc
	v_mul_f32_e32 v48, v48, v66
	v_mul_f32_e32 v49, v49, v66
	v_mul_f32_e32 v50, v50, v66
	v_mul_f32_e32 v51, v51, v66
	v_mul_f32_e32 v16, v16, v66
	v_mul_f32_e32 v17, v17, v66
	v_mul_f32_e32 v18, v18, v66
	v_mul_f32_e32 v19, v19, v66
	v_mul_f32_e32 v0, v0, v66
	v_mul_f32_e32 v1, v1, v66
	v_mul_f32_e32 v2, v2, v66
	v_mul_f32_e32 v3, v3, v66
	v_mul_f32_e32 v52, v52, v66
	v_mul_f32_e32 v53, v53, v66
	v_mul_f32_e32 v54, v54, v66
	v_mul_f32_e32 v55, v55, v66
	v_mul_f32_e32 v56, v56, v66
	v_mul_f32_e32 v57, v57, v66
	v_mul_f32_e32 v58, v58, v66
	v_mul_f32_e32 v59, v59, v66
	v_mul_f32_e32 v60, v60, v66
	v_mul_f32_e32 v61, v61, v66
	v_mul_f32_e32 v62, v62, v66
	v_mul_f32_e32 v63, v63, v66
	v_mul_f32_e32 v67, v32, v66
	v_mul_f32_e32 v68, v33, v66
	v_mul_f32_e32 v69, v34, v66
	v_mul_f32_e32 v70, v35, v66
	v_max_f32_e32 v32, 0, v48
	v_max_f32_e32 v33, 0, v49
	v_max_f32_e32 v34, 0, v50
	v_max_f32_e32 v35, 0, v51
	v_max_f32_e32 v16, 0, v16
	v_max_f32_e32 v17, 0, v17
	v_max_f32_e32 v18, 0, v18
	v_max_f32_e32 v19, 0, v19
	v_max_f32_e32 v0, 0, v0
	v_max_f32_e32 v1, 0, v1
	v_max_f32_e32 v2, 0, v2
	v_max_f32_e32 v3, 0, v3
	v_mul_f32_e32 v71, v36, v66
	v_mul_f32_e32 v72, v37, v66
	v_mul_f32_e32 v73, v38, v66
	v_mul_f32_e32 v74, v39, v66
	v_max_f32_e32 v36, 0, v52
	v_max_f32_e32 v37, 0, v53
	v_max_f32_e32 v38, 0, v54
	v_max_f32_e32 v39, 0, v55
	v_max_f32_e32 v48, 0, v56
	v_max_f32_e32 v49, 0, v57
	v_max_f32_e32 v50, 0, v58
	v_max_f32_e32 v51, 0, v59
	v_max_f32_e32 v52, 0, v60
	v_max_f32_e32 v53, 0, v61
	v_max_f32_e32 v54, 0, v62
	v_max_f32_e32 v55, 0, v63
	v_max_f32_e32 v56, 0, v67
	v_max_f32_e32 v57, 0, v68
	v_max_f32_e32 v58, 0, v69
	v_max_f32_e32 v59, 0, v70
	v_pk_mul_f32 v[32:33], v[32:33], v[32:33]
	v_pk_mul_f32 v[34:35], v[34:35], v[34:35]
	v_pk_mul_f32 v[16:17], v[16:17], v[16:17]
	v_pk_mul_f32 v[18:19], v[18:19], v[18:19]
	v_pk_mul_f32 v[0:1], v[0:1], v[0:1]
	v_pk_mul_f32 v[2:3], v[2:3], v[2:3]
; DEV uint32_t pk2(float lo, float hi) { f32x2 v; v[0] = lo; v[1] = hi; bf16v2 b = __builtin_convertvector(v, bf16v2); return __builtin_bit_cast(uint32_t, b); }
; template <int EPI>
; DEV void gemm_mini(CParams& p, int layer, const bf16_t* __restrict__ A, int lda, const bf16_t* __restrict__ Bt, int K, int n0, char* lds, const int swave) {
;     ...
; #pragma unroll
;     for (int j = 0; j < 4; ++j)
; #pragma unroll
;       for (int g = 0; g < 4; ++g) {
;         const int n = n0 + j * 32 + 8 * g + 4 * hh;
;         float v0 = fmaxf(acc[j][4 * g] * rs, 0.f), v1 = fmaxf(acc[j][4 * g + 1] * rs, 0.f), v2 = fmaxf(acc[j][4 * g + 2] * rs, 0.f), v3 = fmaxf(acc[j][4 * g + 3] * rs, 0.f);
;         u32x2 pk; pk[0] = pk2(v0 * v0, v1 * v1); pk[1] = pk2(v2 * v2, v3 * v3);
;         *(u32x2*)(urow + n) = pk;
;       }
	v_pk_mul_f32 v[36:37], v[36:37], v[36:37]
	v_pk_mul_f32 v[38:39], v[38:39], v[38:39]
	v_pk_mul_f32 v[48:49], v[48:49], v[48:49]
	v_pk_mul_f32 v[50:51], v[50:51], v[50:51]
	v_pk_mul_f32 v[52:53], v[52:53], v[52:53]
	v_pk_mul_f32 v[54:55], v[54:55], v[54:55]
	v_pk_mul_f32 v[56:57], v[56:57], v[56:57]
	v_pk_mul_f32 v[58:59], v[58:59], v[58:59]
	v_cvt_pk_bf16_f32 v32, v32, v33
	v_cvt_pk_bf16_f32 v33, v34, v35
	v_cvt_pk_bf16_f32 v16, v16, v17
	v_cvt_pk_bf16_f32 v17, v18, v19
	v_cvt_pk_bf16_f32 v0, v0, v1
	v_cvt_pk_bf16_f32 v1, v2, v3
	v_cvt_pk_bf16_f32 v34, v36, v37
	v_cvt_pk_bf16_f32 v35, v38, v39
	v_cvt_pk_bf16_f32 v36, v48, v49
	v_cvt_pk_bf16_f32 v37, v50, v51
	v_cvt_pk_bf16_f32 v38, v52, v53
	v_cvt_pk_bf16_f32 v39, v54, v55
	v_cvt_pk_bf16_f32 v48, v56, v57
	v_cvt_pk_bf16_f32 v49, v58, v59
	global_store_dwordx2 v[64:65], v[32:33], off
	global_store_dwordx2 v[64:65], v[34:35], off offset:16
	global_store_dwordx2 v[64:65], v[36:37], off offset:32
	global_store_dwordx2 v[64:65], v[38:39], off offset:48
	global_store_dwordx2 v[64:65], v[48:49], off offset:64
	global_store_dwordx2 v[64:65], v[16:17], off offset:128
	v_mul_f32_e32 v16, v20, v66
	v_mul_f32_e32 v17, v21, v66
	v_mul_f32_e32 v18, v22, v66
	v_mul_f32_e32 v19, v23, v66
	global_store_dwordx2 v[64:65], v[0:1], off offset:192
	v_mul_f32_e32 v0, v4, v66
	v_mul_f32_e32 v1, v5, v66
	v_mul_f32_e32 v2, v6, v66
	v_mul_f32_e32 v3, v7, v66
	v_max_f32_e32 v60, 0, v71
	v_max_f32_e32 v61, 0, v72
	v_max_f32_e32 v62, 0, v73
	v_max_f32_e32 v63, 0, v74
	v_max_f32_e32 v16, 0, v16
	v_max_f32_e32 v17, 0, v17
	v_max_f32_e32 v18, 0, v18
	v_max_f32_e32 v19, 0, v19
	v_max_f32_e32 v0, 0, v0
	v_max_f32_e32 v1, 0, v1
	v_max_f32_e32 v2, 0, v2
	v_max_f32_e32 v3, 0, v3
	v_pk_mul_f32 v[60:61], v[60:61], v[60:61]
	v_pk_mul_f32 v[34:35], v[62:63], v[62:63]
	v_pk_mul_f32 v[16:17], v[16:17], v[16:17]
	v_pk_mul_f32 v[18:19], v[18:19], v[18:19]
	v_pk_mul_f32 v[0:1], v[0:1], v[0:1]
	v_pk_mul_f32 v[2:3], v[2:3], v[2:3]
	v_cvt_pk_bf16_f32 v32, v60, v61
	v_cvt_pk_bf16_f32 v33, v34, v35
	v_cvt_pk_bf16_f32 v16, v16, v17
	v_cvt_pk_bf16_f32 v17, v18, v19
	v_cvt_pk_bf16_f32 v0, v0, v1
	v_cvt_pk_bf16_f32 v1, v2, v3
	global_store_dwordx2 v[64:65], v[32:33], off offset:80
	v_mul_f32_e32 v32, v40, v66
	v_mul_f32_e32 v33, v41, v66
	v_mul_f32_e32 v34, v42, v66
	v_mul_f32_e32 v35, v43, v66
	global_store_dwordx2 v[64:65], v[16:17], off offset:144
	v_mul_f32_e32 v16, v24, v66
	v_mul_f32_e32 v17, v25, v66
	v_mul_f32_e32 v18, v26, v66
	v_mul_f32_e32 v19, v27, v66
	global_store_dwordx2 v[64:65], v[0:1], off offset:208
	v_mul_f32_e32 v0, v8, v66
	v_mul_f32_e32 v1, v9, v66
	v_mul_f32_e32 v2, v10, v66
	v_mul_f32_e32 v3, v11, v66
	v_max_f32_e32 v32, 0, v32
	v_max_f32_e32 v33, 0, v33
	v_max_f32_e32 v34, 0, v34
	v_max_f32_e32 v35, 0, v35
	v_max_f32_e32 v16, 0, v16
	v_max_f32_e32 v17, 0, v17
	v_max_f32_e32 v18, 0, v18
	v_max_f32_e32 v19, 0, v19
	v_max_f32_e32 v0, 0, v0
	v_max_f32_e32 v1, 0, v1
	v_max_f32_e32 v2, 0, v2
	v_max_f32_e32 v3, 0, v3
	v_pk_mul_f32 v[32:33], v[32:33], v[32:33]
	v_pk_mul_f32 v[34:35], v[34:35], v[34:35]
	v_pk_mul_f32 v[16:17], v[16:17], v[16:17]
	v_pk_mul_f32 v[18:19], v[18:19], v[18:19]
	v_pk_mul_f32 v[0:1], v[0:1], v[0:1]
	v_pk_mul_f32 v[2:3], v[2:3], v[2:3]
	v_cvt_pk_bf16_f32 v32, v32, v33
	v_cvt_pk_bf16_f32 v33, v34, v35
	v_cvt_pk_bf16_f32 v16, v16, v17
	v_cvt_pk_bf16_f32 v17, v18, v19
	v_cvt_pk_bf16_f32 v0, v0, v1
	v_cvt_pk_bf16_f32 v1, v2, v3
	global_store_dwordx2 v[64:65], v[32:33], off offset:96
	v_mul_f32_e32 v32, v44, v66
	v_mul_f32_e32 v33, v45, v66
	v_mul_f32_e32 v34, v46, v66
	v_mul_f32_e32 v35, v47, v66
	global_store_dwordx2 v[64:65], v[16:17], off offset:160
	v_mul_f32_e32 v16, v28, v66
	v_mul_f32_e32 v17, v29, v66
	v_mul_f32_e32 v18, v30, v66
	v_mul_f32_e32 v19, v31, v66
	global_store_dwordx2 v[64:65], v[0:1], off offset:224
	v_mul_f32_e32 v0, v12, v66
	v_mul_f32_e32 v1, v13, v66
	v_mul_f32_e32 v2, v14, v66
	v_mul_f32_e32 v3, v15, v66
	v_max_f32_e32 v32, 0, v32
	v_max_f32_e32 v33, 0, v33
	v_max_f32_e32 v34, 0, v34
	v_max_f32_e32 v35, 0, v35
	v_max_f32_e32 v16, 0, v16
	v_max_f32_e32 v17, 0, v17
	v_max_f32_e32 v18, 0, v18
	v_max_f32_e32 v19, 0, v19
	v_max_f32_e32 v0, 0, v0
	v_max_f32_e32 v1, 0, v1
	v_max_f32_e32 v2, 0, v2
	v_max_f32_e32 v3, 0, v3
	v_pk_mul_f32 v[32:33], v[32:33], v[32:33]
	v_pk_mul_f32 v[34:35], v[34:35], v[34:35]
	v_pk_mul_f32 v[16:17], v[16:17], v[16:17]
	v_pk_mul_f32 v[18:19], v[18:19], v[18:19]
	v_pk_mul_f32 v[0:1], v[0:1], v[0:1]
	v_pk_mul_f32 v[2:3], v[2:3], v[2:3]
	v_cvt_pk_bf16_f32 v32, v32, v33
	v_cvt_pk_bf16_f32 v33, v34, v35
	v_cvt_pk_bf16_f32 v16, v16, v17
	v_cvt_pk_bf16_f32 v17, v18, v19
	v_cvt_pk_bf16_f32 v0, v0, v1
	v_cvt_pk_bf16_f32 v1, v2, v3
	global_store_dwordx2 v[64:65], v[32:33], off offset:112
	global_store_dwordx2 v[64:65], v[16:17], off offset:176
	global_store_dwordx2 v[64:65], v[0:1], off offset:240
	s_cbranch_scc0 .LBB0_152

; #define MLOAD(S, kt) { _Pragma("unroll") for (int i = 0; i < 4; ++i) { ra[S][i] = *(const u32x4*)(abase + ((size_t)(32 * i) * lda + (kt) * 64) * 2 + aoff); rb[S][i] = *(const u32x4*)(bbase + ((size_t)(32 * i) * K + (kt) * 64) * 2 + boff); } }
; #define MWRITE(S, buf) { char* as_ = lds + (buf) * 2 * GM_T; char* bs_ = as_ + GM_T; _Pragma("unroll") for (int i = 0; i < 4; ++i) { *(u32x4*)(as_ + (lrow + 32 * i) * GS_B + lch * 16) = ra[S][i]; *(u32x4*)(bs_ + (lrow + 32 * i) * GS_B + lch * 16) = rb[S][i]; } }
; template <int EPI>
; DEV void gemm_mini(CParams& p, int layer, const bf16_t* __restrict__ A, int lda, const bf16_t* __restrict__ Bt, int K, int n0, char* lds, const int swave) {
;     ...
;   MLOAD(0, 0) MLOAD(1, 1) MLOAD(2, 2) MLOAD(3, 3) MWRITE(0, 0) __syncthreads();
; #pragma unroll 1
;   for (int kt = 0; kt < nk; kt += 4) { MSTEP(0, kt) MSTEP(1, kt + 1) MSTEP(2, kt + 2) MSTEP(3, kt + 3) }
.LBB0_142:
	s_add_i32 s29, s29, 4
	s_cmp_lt_u32 s29, 12
	s_cselect_b64 s[60:61], -1, 0
	s_cmp_gt_u32 s29, 11
	s_cselect_b64 s[56:57], -1, 0
	s_and_b64 vcc, exec, s[56:57]
	v_lshl_add_u64 v[0:1], v[64:65], 0, s[94:95]
	v_add_co_u32_e32 v2, vcc, 0xfffd0000, v64
	s_nop 1
	v_addc_co_u32_e32 v3, vcc, -1, v65, vcc
	global_load_dwordx4 v[74:77], v[2:3], off offset:-384
	v_add_co_u32_e32 v2, vcc, 0xf7f90000, v0
	s_nop 1
	v_addc_co_u32_e32 v3, vcc, -1, v1, vcc
	global_load_dwordx4 v[78:81], v[2:3], off offset:-384
	v_add_co_u32_e32 v2, vcc, 0xfffe0000, v64
	s_nop 1
	v_addc_co_u32_e32 v3, vcc, -1, v65, vcc
	global_load_dwordx4 v[82:85], v[2:3], off offset:-384
	v_add_co_u32_e32 v2, vcc, 0xf7fa0000, v0
	s_nop 1
	v_addc_co_u32_e32 v3, vcc, -1, v1, vcc
	global_load_dwordx4 v[90:93], v[2:3], off offset:-384
	v_add_co_u32_e32 v2, vcc, 0xffff0000, v64
	s_nop 1
	v_addc_co_u32_e32 v3, vcc, -1, v65, vcc
	global_load_dwordx4 v[98:101], v[2:3], off offset:-384
	v_add_co_u32_e32 v2, vcc, 0xf7fb0000, v0
	s_nop 1
	v_addc_co_u32_e32 v3, vcc, -1, v1, vcc
	global_load_dwordx4 v[110:113], v[2:3], off offset:-384
	global_load_dwordx4 v[126:129], v[64:65], off offset:-384
	v_add_co_u32_e32 v2, vcc, 0xf7fc0000, v0
	s_nop 1
	v_addc_co_u32_e32 v3, vcc, -1, v1, vcc
	global_load_dwordx4 v[146:149], v[2:3], off offset:-384
.LBB0_144:
	s_cmp_gt_u32 s29, 10
	ds_read_b128 v[204:207], v71
	ds_read_b128 v[208:211], v69 offset:18432
	ds_read_b128 v[212:215], v69 offset:23040
	ds_read_b128 v[216:219], v69 offset:27648
	ds_read_b128 v[220:223], v69 offset:32256
	ds_read_b128 v[224:227], v71 offset:32
	ds_read_b128 v[228:231], v69 offset:18464
	ds_read_b128 v[232:235], v69 offset:23072
	ds_read_b128 v[236:239], v69 offset:27680
	ds_read_b128 v[244:247], v69 offset:32288
	s_waitcnt lgkmcnt(5)
	v_mfma_f32_32x32x16_bf16 a[0:15], v[208:211], v[204:207], a[0:15]
	v_mfma_f32_32x32x16_bf16 a[16:31], v[212:215], v[204:207], a[16:31]
	v_mfma_f32_32x32x16_bf16 a[32:47], v[216:219], v[204:207], a[32:47]
	v_mfma_f32_32x32x16_bf16 a[48:63], v[220:223], v[204:207], a[48:63]
	ds_read_b128 v[204:207], v71 offset:64
	ds_read_b128 v[208:211], v69 offset:18496
	ds_read_b128 v[212:215], v69 offset:23104
	ds_read_b128 v[216:219], v69 offset:27712
	ds_read_b128 v[220:223], v69 offset:32320
	s_waitcnt lgkmcnt(5)
	v_mfma_f32_32x32x16_bf16 a[0:15], v[228:231], v[224:227], a[0:15]
	v_mfma_f32_32x32x16_bf16 a[16:31], v[232:235], v[224:227], a[16:31]
	v_mfma_f32_32x32x16_bf16 a[32:47], v[236:239], v[224:227], a[32:47]
	v_mfma_f32_32x32x16_bf16 a[48:63], v[244:247], v[224:227], a[48:63]
	ds_read_b128 v[224:227], v71 offset:96
	ds_read_b128 v[228:231], v69 offset:18528
	ds_read_b128 v[232:235], v69 offset:23136
	ds_read_b128 v[236:239], v69 offset:27744
	ds_read_b128 v[244:247], v69 offset:32352
	s_waitcnt lgkmcnt(5)
	v_mfma_f32_32x32x16_bf16 a[0:15], v[208:211], v[204:207], a[0:15]
	v_mfma_f32_32x32x16_bf16 a[16:31], v[212:215], v[204:207], a[16:31]
	v_mfma_f32_32x32x16_bf16 a[32:47], v[216:219], v[204:207], a[32:47]
	v_mfma_f32_32x32x16_bf16 a[48:63], v[220:223], v[204:207], a[48:63]
	s_waitcnt lgkmcnt(0)
	v_mfma_f32_32x32x16_bf16 a[0:15], v[228:231], v[224:227], a[0:15]
	v_mfma_f32_32x32x16_bf16 a[16:31], v[232:235], v[224:227], a[16:31]
	v_mfma_f32_32x32x16_bf16 a[32:47], v[236:239], v[224:227], a[32:47]
	v_mfma_f32_32x32x16_bf16 a[48:63], v[244:247], v[224:227], a[48:63]
	s_waitcnt vmcnt(24)
	ds_write_b128 v67, v[86:89] offset:36864
	ds_write_b128 v67, v[94:97] offset:55296
	ds_write_b128 v67, v[106:109] offset:41472
	ds_write_b128 v67, v[122:125] offset:59904
	ds_write_b128 v67, v[134:137] offset:46080
	ds_write_b128 v67, v[154:157] offset:64512
	ds_write_b128 v67, v[162:165] offset:50688
	ds_write_b128 v72, v[174:177] offset:55296
	s_waitcnt lgkmcnt(0)
	s_barrier
	v_add_co_u32_e32 v2, vcc, 0xfffd0000, v64
	s_nop 1
	v_addc_co_u32_e32 v3, vcc, -1, v65, vcc
	global_load_dwordx4 v[86:89], v[2:3], off offset:-256
	v_add_co_u32_e32 v2, vcc, 0xf7f90000, v0
	s_nop 1
	v_addc_co_u32_e32 v3, vcc, -1, v1, vcc
	global_load_dwordx4 v[94:97], v[2:3], off offset:-256
	v_add_co_u32_e32 v2, vcc, 0xfffe0000, v64
	s_nop 1
	v_addc_co_u32_e32 v3, vcc, -1, v65, vcc
	global_load_dwordx4 v[106:109], v[2:3], off offset:-256
	v_add_co_u32_e32 v2, vcc, 0xf7fa0000, v0
	s_nop 1
	v_addc_co_u32_e32 v3, vcc, -1, v1, vcc
	global_load_dwordx4 v[122:125], v[2:3], off offset:-256
	v_add_co_u32_e32 v2, vcc, 0xffff0000, v64
	s_nop 1
	v_addc_co_u32_e32 v3, vcc, -1, v65, vcc
	global_load_dwordx4 v[134:137], v[2:3], off offset:-256
	v_add_co_u32_e32 v2, vcc, 0xf7fb0000, v0
	s_nop 1
	v_addc_co_u32_e32 v3, vcc, -1, v1, vcc
	global_load_dwordx4 v[154:157], v[2:3], off offset:-256
	global_load_dwordx4 v[162:165], v[64:65], off offset:-256
	v_add_co_u32_e32 v2, vcc, 0xf7fc0000, v0
	s_nop 1
	v_addc_co_u32_e32 v3, vcc, -1, v1, vcc
	global_load_dwordx4 v[174:177], v[2:3], off offset:-256
; #define MLOAD(S, kt) { _Pragma("unroll") for (int i = 0; i < 4; ++i) { ra[S][i] = *(const u32x4*)(abase + ((size_t)(32 * i) * lda + (kt) * 64) * 2 + aoff); rb[S][i] = *(const u32x4*)(bbase + ((size_t)(32 * i) * K + (kt) * 64) * 2 + boff); } }
; #define MWRITE(S, buf) { char* as_ = lds + (buf) * 2 * GM_T; char* bs_ = as_ + GM_T; _Pragma("unroll") for (int i = 0; i < 4; ++i) { *(u32x4*)(as_ + (lrow + 32 * i) * GS_B + lch * 16) = ra[S][i]; *(u32x4*)(bs_ + (lrow + 32 * i) * GS_B + lch * 16) = rb[S][i]; } }
; template <int EPI>
; DEV void gemm_mini(CParams& p, int layer, const bf16_t* __restrict__ A, int lda, const bf16_t* __restrict__ Bt, int K, int n0, char* lds, const int swave) {
;     ...
;   MLOAD(0, 0) MLOAD(1, 1) MLOAD(2, 2) MLOAD(3, 3) MWRITE(0, 0) __syncthreads();
; #pragma unroll 1
;   for (int kt = 0; kt < nk; kt += 4) { MSTEP(0, kt) MSTEP(1, kt + 1) MSTEP(2, kt + 2) MSTEP(3, kt + 3) }
.LBB0_146:
	s_cmp_gt_u32 s29, 9
	ds_read_b128 v[204:207], v71 offset:36864
	ds_read_b128 v[208:211], v69 offset:55296
	ds_read_b128 v[212:215], v69 offset:59904
	ds_read_b128 v[216:219], v69 offset:64512
	ds_read_b128 v[220:223], v70 offset:13824
	ds_read_b128 v[224:227], v71 offset:36896
	ds_read_b128 v[228:231], v69 offset:55328
	ds_read_b128 v[232:235], v69 offset:59936
	ds_read_b128 v[236:239], v69 offset:64544
	ds_read_b128 v[244:247], v70 offset:13856
	s_waitcnt lgkmcnt(5)
	v_mfma_f32_32x32x16_bf16 a[0:15], v[208:211], v[204:207], a[0:15]
	v_mfma_f32_32x32x16_bf16 a[16:31], v[212:215], v[204:207], a[16:31]
	v_mfma_f32_32x32x16_bf16 a[32:47], v[216:219], v[204:207], a[32:47]
	v_mfma_f32_32x32x16_bf16 a[48:63], v[220:223], v[204:207], a[48:63]
	ds_read_b128 v[204:207], v71 offset:36928
	ds_read_b128 v[208:211], v69 offset:55360
	ds_read_b128 v[212:215], v69 offset:59968
	ds_read_b128 v[216:219], v69 offset:64576
	ds_read_b128 v[220:223], v70 offset:13888
	s_waitcnt lgkmcnt(5)
	v_mfma_f32_32x32x16_bf16 a[0:15], v[228:231], v[224:227], a[0:15]
	v_mfma_f32_32x32x16_bf16 a[16:31], v[232:235], v[224:227], a[16:31]
	v_mfma_f32_32x32x16_bf16 a[32:47], v[236:239], v[224:227], a[32:47]
	v_mfma_f32_32x32x16_bf16 a[48:63], v[244:247], v[224:227], a[48:63]
	ds_read_b128 v[224:227], v71 offset:36960
	ds_read_b128 v[228:231], v69 offset:55392
	ds_read_b128 v[232:235], v69 offset:60000
	ds_read_b128 v[236:239], v69 offset:64608
	ds_read_b128 v[244:247], v70 offset:13920
	s_waitcnt lgkmcnt(5)
	v_mfma_f32_32x32x16_bf16 a[0:15], v[208:211], v[204:207], a[0:15]
	v_mfma_f32_32x32x16_bf16 a[16:31], v[212:215], v[204:207], a[16:31]
	v_mfma_f32_32x32x16_bf16 a[32:47], v[216:219], v[204:207], a[32:47]
	v_mfma_f32_32x32x16_bf16 a[48:63], v[220:223], v[204:207], a[48:63]
	s_waitcnt lgkmcnt(0)
	v_mfma_f32_32x32x16_bf16 a[0:15], v[228:231], v[224:227], a[0:15]
	v_mfma_f32_32x32x16_bf16 a[16:31], v[232:235], v[224:227], a[16:31]
	v_mfma_f32_32x32x16_bf16 a[32:47], v[236:239], v[224:227], a[32:47]
	v_mfma_f32_32x32x16_bf16 a[48:63], v[244:247], v[224:227], a[48:63]
	s_waitcnt vmcnt(24)
	ds_write_b128 v67, v[102:105]
	ds_write_b128 v67, v[114:117] offset:18432
	ds_write_b128 v67, v[130:133] offset:4608
	ds_write_b128 v67, v[142:145] offset:23040
	ds_write_b128 v67, v[158:161] offset:9216
	ds_write_b128 v67, v[170:173] offset:27648
	ds_write_b128 v67, v[182:185] offset:13824
	ds_write_b128 v67, v[186:189] offset:32256
	s_waitcnt lgkmcnt(0)
	s_barrier
	v_add_co_u32_e32 v2, vcc, 0xfffd0000, v64
	s_nop 1
	v_addc_co_u32_e32 v3, vcc, -1, v65, vcc
	global_load_dwordx4 v[102:105], v[2:3], off offset:-128
	v_add_co_u32_e32 v2, vcc, 0xf7f90000, v0
	s_nop 1
	v_addc_co_u32_e32 v3, vcc, -1, v1, vcc
	global_load_dwordx4 v[114:117], v[2:3], off offset:-128
	v_add_co_u32_e32 v2, vcc, 0xfffe0000, v64
	s_nop 1
	v_addc_co_u32_e32 v3, vcc, -1, v65, vcc
	global_load_dwordx4 v[130:133], v[2:3], off offset:-128
	v_add_co_u32_e32 v2, vcc, 0xf7fa0000, v0
	s_nop 1
	v_addc_co_u32_e32 v3, vcc, -1, v1, vcc
	global_load_dwordx4 v[142:145], v[2:3], off offset:-128
	v_add_co_u32_e32 v2, vcc, 0xffff0000, v64
	s_nop 1
	v_addc_co_u32_e32 v3, vcc, -1, v65, vcc
	global_load_dwordx4 v[158:161], v[2:3], off offset:-128
	v_add_co_u32_e32 v2, vcc, 0xf7fb0000, v0
	s_nop 1
	v_addc_co_u32_e32 v3, vcc, -1, v1, vcc
	global_load_dwordx4 v[170:173], v[2:3], off offset:-128
	global_load_dwordx4 v[182:185], v[64:65], off offset:-128
	v_add_co_u32_e32 v2, vcc, 0xf7fc0000, v0
	s_nop 1
	v_addc_co_u32_e32 v3, vcc, -1, v1, vcc
	global_load_dwordx4 v[186:189], v[2:3], off offset:-128
; #define MLOAD(S, kt) { _Pragma("unroll") for (int i = 0; i < 4; ++i) { ra[S][i] = *(const u32x4*)(abase + ((size_t)(32 * i) * lda + (kt) * 64) * 2 + aoff); rb[S][i] = *(const u32x4*)(bbase + ((size_t)(32 * i) * K + (kt) * 64) * 2 + boff); } }
; #define MWRITE(S, buf) { char* as_ = lds + (buf) * 2 * GM_T; char* bs_ = as_ + GM_T; _Pragma("unroll") for (int i = 0; i < 4; ++i) { *(u32x4*)(as_ + (lrow + 32 * i) * GS_B + lch * 16) = ra[S][i]; *(u32x4*)(bs_ + (lrow + 32 * i) * GS_B + lch * 16) = rb[S][i]; } }
; template <int EPI>
; DEV void gemm_mini(CParams& p, int layer, const bf16_t* __restrict__ A, int lda, const bf16_t* __restrict__ Bt, int K, int n0, char* lds, const int swave) {
;     ...
;   MLOAD(0, 0) MLOAD(1, 1) MLOAD(2, 2) MLOAD(3, 3) MWRITE(0, 0) __syncthreads();
; #pragma unroll 1
;   for (int kt = 0; kt < nk; kt += 4) { MSTEP(0, kt) MSTEP(1, kt + 1) MSTEP(2, kt + 2) MSTEP(3, kt + 3) }
.LBB0_148:
	s_cmp_gt_u32 s29, 8
	ds_read_b128 v[204:207], v71
	ds_read_b128 v[208:211], v69 offset:18432
	ds_read_b128 v[212:215], v69 offset:23040
	ds_read_b128 v[216:219], v69 offset:27648
	ds_read_b128 v[220:223], v69 offset:32256
	ds_read_b128 v[224:227], v71 offset:32
	ds_read_b128 v[228:231], v69 offset:18464
	ds_read_b128 v[232:235], v69 offset:23072
	ds_read_b128 v[236:239], v69 offset:27680
	ds_read_b128 v[244:247], v69 offset:32288
	s_waitcnt lgkmcnt(5)
	v_mfma_f32_32x32x16_bf16 a[0:15], v[208:211], v[204:207], a[0:15]
	v_mfma_f32_32x32x16_bf16 a[16:31], v[212:215], v[204:207], a[16:31]
	v_mfma_f32_32x32x16_bf16 a[32:47], v[216:219], v[204:207], a[32:47]
	v_mfma_f32_32x32x16_bf16 a[48:63], v[220:223], v[204:207], a[48:63]
	ds_read_b128 v[204:207], v71 offset:64
	ds_read_b128 v[208:211], v69 offset:18496
	ds_read_b128 v[212:215], v69 offset:23104
	ds_read_b128 v[216:219], v69 offset:27712
	ds_read_b128 v[220:223], v69 offset:32320
	s_waitcnt lgkmcnt(5)
	v_mfma_f32_32x32x16_bf16 a[0:15], v[228:231], v[224:227], a[0:15]
	v_mfma_f32_32x32x16_bf16 a[16:31], v[232:235], v[224:227], a[16:31]
	v_mfma_f32_32x32x16_bf16 a[32:47], v[236:239], v[224:227], a[32:47]
	v_mfma_f32_32x32x16_bf16 a[48:63], v[244:247], v[224:227], a[48:63]
	ds_read_b128 v[224:227], v71 offset:96
	ds_read_b128 v[228:231], v69 offset:18528
	ds_read_b128 v[232:235], v69 offset:23136
	ds_read_b128 v[236:239], v69 offset:27744
	ds_read_b128 v[244:247], v69 offset:32352
	s_waitcnt lgkmcnt(5)
	v_mfma_f32_32x32x16_bf16 a[0:15], v[208:211], v[204:207], a[0:15]
	v_mfma_f32_32x32x16_bf16 a[16:31], v[212:215], v[204:207], a[16:31]
	v_mfma_f32_32x32x16_bf16 a[32:47], v[216:219], v[204:207], a[32:47]
	v_mfma_f32_32x32x16_bf16 a[48:63], v[220:223], v[204:207], a[48:63]
	s_waitcnt lgkmcnt(0)
	v_mfma_f32_32x32x16_bf16 a[0:15], v[228:231], v[224:227], a[0:15]
	v_mfma_f32_32x32x16_bf16 a[16:31], v[232:235], v[224:227], a[16:31]
	v_mfma_f32_32x32x16_bf16 a[32:47], v[236:239], v[224:227], a[32:47]
	v_mfma_f32_32x32x16_bf16 a[48:63], v[244:247], v[224:227], a[48:63]
	s_waitcnt vmcnt(24)
	ds_write_b128 v67, v[118:121] offset:36864
	ds_write_b128 v67, v[138:141] offset:55296
	ds_write_b128 v67, v[150:153] offset:41472
	ds_write_b128 v67, v[166:169] offset:59904
	ds_write_b128 v67, v[178:181] offset:46080
	ds_write_b128 v67, v[190:193] offset:64512
	ds_write_b128 v67, v[194:197] offset:50688
	ds_write_b128 v72, v[198:201] offset:55296
	s_waitcnt lgkmcnt(0)
	s_barrier
	v_add_co_u32_e32 v2, vcc, 0xfffd0000, v64
	s_nop 1
	v_addc_co_u32_e32 v3, vcc, -1, v65, vcc
	global_load_dwordx4 v[118:121], v[2:3], off
	v_add_co_u32_e32 v2, vcc, 0xf7f90000, v0
	s_nop 1
	v_addc_co_u32_e32 v3, vcc, -1, v1, vcc
	global_load_dwordx4 v[138:141], v[2:3], off
	v_add_co_u32_e32 v2, vcc, 0xfffe0000, v64
	s_nop 1
	v_addc_co_u32_e32 v3, vcc, -1, v65, vcc
	global_load_dwordx4 v[150:153], v[2:3], off
	v_add_co_u32_e32 v2, vcc, 0xf7fa0000, v0
	s_nop 1
	v_addc_co_u32_e32 v3, vcc, -1, v1, vcc
	global_load_dwordx4 v[166:169], v[2:3], off
	v_add_co_u32_e32 v2, vcc, 0xffff0000, v64
	s_nop 1
	v_addc_co_u32_e32 v3, vcc, -1, v65, vcc
	global_load_dwordx4 v[178:181], v[2:3], off
	v_add_co_u32_e32 v2, vcc, 0xf7fb0000, v0
	s_nop 1
	v_addc_co_u32_e32 v3, vcc, -1, v1, vcc
	v_add_co_u32_e32 v0, vcc, 0xf7fc0000, v0
	global_load_dwordx4 v[190:193], v[2:3], off
	global_load_dwordx4 v[194:197], v[64:65], off
	v_addc_co_u32_e32 v1, vcc, -1, v1, vcc
	global_load_dwordx4 v[198:201], v[0:1], off
.LBB0_150:
	s_andn2_b64 vcc, exec, s[60:61]
	ds_read_b128 v[204:207], v71 offset:36864
	ds_read_b128 v[208:211], v69 offset:55296
	ds_read_b128 v[212:215], v69 offset:59904
	ds_read_b128 v[216:219], v69 offset:64512
	ds_read_b128 v[220:223], v70 offset:13824
	ds_read_b128 v[224:227], v71 offset:36896
	ds_read_b128 v[228:231], v69 offset:55328
	ds_read_b128 v[232:235], v69 offset:59936
	ds_read_b128 v[236:239], v69 offset:64544
	ds_read_b128 v[244:247], v70 offset:13856
	s_waitcnt lgkmcnt(5)
	v_mfma_f32_32x32x16_bf16 a[0:15], v[208:211], v[204:207], a[0:15]
	v_mfma_f32_32x32x16_bf16 a[16:31], v[212:215], v[204:207], a[16:31]
	v_mfma_f32_32x32x16_bf16 a[32:47], v[216:219], v[204:207], a[32:47]
	v_mfma_f32_32x32x16_bf16 a[48:63], v[220:223], v[204:207], a[48:63]
	ds_read_b128 v[204:207], v71 offset:36928
	ds_read_b128 v[208:211], v69 offset:55360
	ds_read_b128 v[212:215], v69 offset:59968
	ds_read_b128 v[216:219], v69 offset:64576
	ds_read_b128 v[220:223], v70 offset:13888
	s_waitcnt lgkmcnt(5)
	v_mfma_f32_32x32x16_bf16 a[0:15], v[228:231], v[224:227], a[0:15]
	v_mfma_f32_32x32x16_bf16 a[16:31], v[232:235], v[224:227], a[16:31]
	v_mfma_f32_32x32x16_bf16 a[32:47], v[236:239], v[224:227], a[32:47]
	v_mfma_f32_32x32x16_bf16 a[48:63], v[244:247], v[224:227], a[48:63]
	ds_read_b128 v[224:227], v71 offset:36960
	ds_read_b128 v[228:231], v69 offset:55392
	ds_read_b128 v[232:235], v69 offset:60000
	ds_read_b128 v[236:239], v69 offset:64608
	ds_read_b128 v[244:247], v70 offset:13920
	s_waitcnt lgkmcnt(5)
	v_mfma_f32_32x32x16_bf16 a[0:15], v[208:211], v[204:207], a[0:15]
	v_mfma_f32_32x32x16_bf16 a[16:31], v[212:215], v[204:207], a[16:31]
	v_mfma_f32_32x32x16_bf16 a[32:47], v[216:219], v[204:207], a[32:47]
	v_mfma_f32_32x32x16_bf16 a[48:63], v[220:223], v[204:207], a[48:63]
	s_waitcnt lgkmcnt(0)
	v_mfma_f32_32x32x16_bf16 a[0:15], v[228:231], v[224:227], a[0:15]
	v_mfma_f32_32x32x16_bf16 a[16:31], v[232:235], v[224:227], a[16:31]
	v_mfma_f32_32x32x16_bf16 a[32:47], v[236:239], v[224:227], a[32:47]
	v_mfma_f32_32x32x16_bf16 a[48:63], v[244:247], v[224:227], a[48:63]
	s_cbranch_vccnz .LBB0_141
	s_waitcnt vmcnt(24)
	ds_write_b128 v67, v[74:77]
	ds_write_b128 v67, v[78:81] offset:18432
	ds_write_b128 v67, v[82:85] offset:4608
	ds_write_b128 v67, v[90:93] offset:23040
	ds_write_b128 v67, v[98:101] offset:9216
	ds_write_b128 v67, v[110:113] offset:27648
	ds_write_b128 v67, v[126:129] offset:13824
	ds_write_b128 v67, v[146:149] offset:32256
	s_branch .LBB0_141

; #define MLOAD(S, kt) { _Pragma("unroll") for (int i = 0; i < 4; ++i) { ra[S][i] = *(const u32x4*)(abase + ((size_t)(32 * i) * lda + (kt) * 64) * 2 + aoff); rb[S][i] = *(const u32x4*)(bbase + ((size_t)(32 * i) * K + (kt) * 64) * 2 + boff); } }
; #define MWRITE(S, buf) { char* as_ = lds + (buf) * 2 * GM_T; char* bs_ = as_ + GM_T; _Pragma("unroll") for (int i = 0; i < 4; ++i) { *(u32x4*)(as_ + (lrow + 32 * i) * GS_B + lch * 16) = ra[S][i]; *(u32x4*)(bs_ + (lrow + 32 * i) * GS_B + lch * 16) = rb[S][i]; } }
; template <int EPI>
; DEV void gemm_mini(CParams& p, int layer, const bf16_t* __restrict__ A, int lda, const bf16_t* __restrict__ Bt, int K, int n0, char* lds, const int swave) {
;     ...
;   MLOAD(0, 0) MLOAD(1, 1) MLOAD(2, 2) MLOAD(3, 3) MWRITE(0, 0) __syncthreads();
; #pragma unroll 1
;   for (int kt = 0; kt < nk; kt += 4) { MSTEP(0, kt) MSTEP(1, kt + 1) MSTEP(2, kt + 2) MSTEP(3, kt + 3) }
.LBB0_210:
	s_add_i32 s30, s29, -3
	s_cmp_lt_u32 s30, s31
	s_cselect_b64 s[60:61], -1, 0
	s_cmp_ge_u32 s30, s31
	v_lshl_add_u64 v[0:1], s[96:97], 0, v[240:241]
	v_lshl_add_u64 v[2:3], s[84:85], 0, v[240:241]
	v_lshl_add_u64 v[4:5], s[94:95], 0, v[240:241]
	v_lshl_add_u64 v[6:7], s[88:89], 0, v[240:241]
	v_lshl_add_u64 v[8:9], s[92:93], 0, v[240:241]
	v_lshl_add_u64 v[10:11], s[90:91], 0, v[240:241]
	v_lshl_add_u64 v[12:13], s[6:7], 0, v[240:241]
	v_lshl_add_u64 v[14:15], s[86:87], 0, v[240:241]
	global_load_dwordx4 v[22:25], v[0:1], off offset:512
	global_load_dwordx4 v[26:29], v[2:3], off offset:512
	global_load_dwordx4 v[30:33], v[4:5], off offset:512
	global_load_dwordx4 v[34:37], v[6:7], off offset:512
	global_load_dwordx4 v[38:41], v[8:9], off offset:512
	global_load_dwordx4 v[42:45], v[10:11], off offset:512
	global_load_dwordx4 v[46:49], v[12:13], off offset:512
	global_load_dwordx4 v[54:57], v[14:15], off offset:512
.LBB0_212:
	s_add_i32 s42, s29, -6
	s_cmp_ge_u32 s42, s31
	ds_read_b128 v[204:207], v19
	ds_read_b128 v[208:211], v17 offset:18432
	ds_read_b128 v[212:215], v17 offset:23040
	ds_read_b128 v[216:219], v17 offset:27648
	ds_read_b128 v[220:223], v17 offset:32256
	ds_read_b128 v[224:227], v19 offset:32
	ds_read_b128 v[228:231], v17 offset:18464
	ds_read_b128 v[232:235], v17 offset:23072
	ds_read_b128 v[236:239], v17 offset:27680
	ds_read_b128 v[244:247], v17 offset:32288
	s_waitcnt lgkmcnt(5)
	v_mfma_f32_32x32x16_bf16 a[0:15], v[208:211], v[204:207], a[0:15]
	v_mfma_f32_32x32x16_bf16 a[16:31], v[212:215], v[204:207], a[16:31]
	v_mfma_f32_32x32x16_bf16 a[32:47], v[216:219], v[204:207], a[32:47]
	v_mfma_f32_32x32x16_bf16 a[48:63], v[220:223], v[204:207], a[48:63]
	ds_read_b128 v[204:207], v19 offset:64
	ds_read_b128 v[208:211], v17 offset:18496
	ds_read_b128 v[212:215], v17 offset:23104
	ds_read_b128 v[216:219], v17 offset:27712
	ds_read_b128 v[220:223], v17 offset:32320
	s_waitcnt lgkmcnt(5)
	v_mfma_f32_32x32x16_bf16 a[0:15], v[228:231], v[224:227], a[0:15]
	v_mfma_f32_32x32x16_bf16 a[16:31], v[232:235], v[224:227], a[16:31]
	v_mfma_f32_32x32x16_bf16 a[32:47], v[236:239], v[224:227], a[32:47]
	v_mfma_f32_32x32x16_bf16 a[48:63], v[244:247], v[224:227], a[48:63]
	ds_read_b128 v[224:227], v19 offset:96
	ds_read_b128 v[228:231], v17 offset:18528
	ds_read_b128 v[232:235], v17 offset:23136
	ds_read_b128 v[236:239], v17 offset:27744
	ds_read_b128 v[244:247], v17 offset:32352
	s_waitcnt lgkmcnt(5)
	v_mfma_f32_32x32x16_bf16 a[0:15], v[208:211], v[204:207], a[0:15]
	v_mfma_f32_32x32x16_bf16 a[16:31], v[212:215], v[204:207], a[16:31]
	v_mfma_f32_32x32x16_bf16 a[32:47], v[216:219], v[204:207], a[32:47]
	v_mfma_f32_32x32x16_bf16 a[48:63], v[220:223], v[204:207], a[48:63]
	s_waitcnt lgkmcnt(0)
	v_mfma_f32_32x32x16_bf16 a[0:15], v[228:231], v[224:227], a[0:15]
	v_mfma_f32_32x32x16_bf16 a[16:31], v[232:235], v[224:227], a[16:31]
	v_mfma_f32_32x32x16_bf16 a[32:47], v[236:239], v[224:227], a[32:47]
	v_mfma_f32_32x32x16_bf16 a[48:63], v[244:247], v[224:227], a[48:63]
	s_cbranch_scc1 .LBB0_214
	s_waitcnt vmcnt(24)
	ds_write_b128 v16, v[50:53] offset:36864
	ds_write_b128 v16, v[58:61] offset:55296
	ds_write_b128 v16, v[66:69] offset:41472
	ds_write_b128 v16, v[70:73] offset:59904
	ds_write_b128 v16, v[74:77] offset:46080
	ds_write_b128 v16, v[78:81] offset:64512
	ds_write_b128 v16, v[82:85] offset:50688
	ds_write_b128 v20, v[94:97] offset:55296
.LBB0_214:
	s_add_i32 s42, s29, -2
	s_cmp_ge_u32 s42, s31
	s_waitcnt lgkmcnt(0)
	s_barrier
	global_load_dwordx4 v[50:53], v[0:1], off offset:640
	global_load_dwordx4 v[58:61], v[2:3], off offset:640
	global_load_dwordx4 v[66:69], v[4:5], off offset:640
	global_load_dwordx4 v[70:73], v[6:7], off offset:640
	global_load_dwordx4 v[74:77], v[8:9], off offset:640
	global_load_dwordx4 v[78:81], v[10:11], off offset:640
	global_load_dwordx4 v[82:85], v[12:13], off offset:640
	global_load_dwordx4 v[94:97], v[14:15], off offset:640
.LBB0_216:
	s_add_i32 s42, s29, -5
	s_cmp_ge_u32 s42, s31
	ds_read_b128 v[204:207], v19 offset:36864
	ds_read_b128 v[208:211], v17 offset:55296
	ds_read_b128 v[212:215], v17 offset:59904
	ds_read_b128 v[216:219], v17 offset:64512
	ds_read_b128 v[220:223], v18 offset:13824
	ds_read_b128 v[224:227], v19 offset:36896
	ds_read_b128 v[228:231], v17 offset:55328
	ds_read_b128 v[232:235], v17 offset:59936
	ds_read_b128 v[236:239], v17 offset:64544
	ds_read_b128 v[244:247], v18 offset:13856
	s_waitcnt lgkmcnt(5)
	v_mfma_f32_32x32x16_bf16 a[0:15], v[208:211], v[204:207], a[0:15]
	v_mfma_f32_32x32x16_bf16 a[16:31], v[212:215], v[204:207], a[16:31]
	v_mfma_f32_32x32x16_bf16 a[32:47], v[216:219], v[204:207], a[32:47]
	v_mfma_f32_32x32x16_bf16 a[48:63], v[220:223], v[204:207], a[48:63]
	ds_read_b128 v[204:207], v19 offset:36928
	ds_read_b128 v[208:211], v17 offset:55360
	ds_read_b128 v[212:215], v17 offset:59968
	ds_read_b128 v[216:219], v17 offset:64576
	ds_read_b128 v[220:223], v18 offset:13888
	s_waitcnt lgkmcnt(5)
	v_mfma_f32_32x32x16_bf16 a[0:15], v[228:231], v[224:227], a[0:15]
	v_mfma_f32_32x32x16_bf16 a[16:31], v[232:235], v[224:227], a[16:31]
	v_mfma_f32_32x32x16_bf16 a[32:47], v[236:239], v[224:227], a[32:47]
	v_mfma_f32_32x32x16_bf16 a[48:63], v[244:247], v[224:227], a[48:63]
	ds_read_b128 v[224:227], v19 offset:36960
	ds_read_b128 v[228:231], v17 offset:55392
	ds_read_b128 v[232:235], v17 offset:60000
	ds_read_b128 v[236:239], v17 offset:64608
	ds_read_b128 v[244:247], v18 offset:13920
	s_waitcnt lgkmcnt(5)
	v_mfma_f32_32x32x16_bf16 a[0:15], v[208:211], v[204:207], a[0:15]
	v_mfma_f32_32x32x16_bf16 a[16:31], v[212:215], v[204:207], a[16:31]
	v_mfma_f32_32x32x16_bf16 a[32:47], v[216:219], v[204:207], a[32:47]
	v_mfma_f32_32x32x16_bf16 a[48:63], v[220:223], v[204:207], a[48:63]
	s_waitcnt lgkmcnt(0)
	v_mfma_f32_32x32x16_bf16 a[0:15], v[228:231], v[224:227], a[0:15]
	v_mfma_f32_32x32x16_bf16 a[16:31], v[232:235], v[224:227], a[16:31]
	v_mfma_f32_32x32x16_bf16 a[32:47], v[236:239], v[224:227], a[32:47]
	v_mfma_f32_32x32x16_bf16 a[48:63], v[244:247], v[224:227], a[48:63]
	s_cbranch_scc1 .LBB0_218
	s_waitcnt vmcnt(24)
	ds_write_b128 v16, v[86:89]
	ds_write_b128 v16, v[90:93] offset:18432
	ds_write_b128 v16, v[98:101] offset:4608
	ds_write_b128 v16, v[102:105] offset:23040
	ds_write_b128 v16, v[106:109] offset:9216
	ds_write_b128 v16, v[110:113] offset:27648
	ds_write_b128 v16, v[118:121] offset:13824
	ds_write_b128 v16, v[122:125] offset:32256
; #define MLOAD(S, kt) { _Pragma("unroll") for (int i = 0; i < 4; ++i) { ra[S][i] = *(const u32x4*)(abase + ((size_t)(32 * i) * lda + (kt) * 64) * 2 + aoff); rb[S][i] = *(const u32x4*)(bbase + ((size_t)(32 * i) * K + (kt) * 64) * 2 + boff); } }
; #define MWRITE(S, buf) { char* as_ = lds + (buf) * 2 * GM_T; char* bs_ = as_ + GM_T; _Pragma("unroll") for (int i = 0; i < 4; ++i) { *(u32x4*)(as_ + (lrow + 32 * i) * GS_B + lch * 16) = ra[S][i]; *(u32x4*)(bs_ + (lrow + 32 * i) * GS_B + lch * 16) = rb[S][i]; } }
; template <int EPI>
; DEV void gemm_mini(CParams& p, int layer, const bf16_t* __restrict__ A, int lda, const bf16_t* __restrict__ Bt, int K, int n0, char* lds, const int swave) {
;     ...
;   MLOAD(0, 0) MLOAD(1, 1) MLOAD(2, 2) MLOAD(3, 3) MWRITE(0, 0) __syncthreads();
; #pragma unroll 1
;   for (int kt = 0; kt < nk; kt += 4) { MSTEP(0, kt) MSTEP(1, kt + 1) MSTEP(2, kt + 2) MSTEP(3, kt + 3) }
.LBB0_218:
	s_add_i32 s42, s29, -1
	s_cmp_ge_u32 s42, s31
	s_waitcnt lgkmcnt(0)
	s_barrier
	global_load_dwordx4 v[86:89], v[0:1], off offset:768
	global_load_dwordx4 v[90:93], v[2:3], off offset:768
	global_load_dwordx4 v[98:101], v[4:5], off offset:768
	global_load_dwordx4 v[102:105], v[6:7], off offset:768
	global_load_dwordx4 v[106:109], v[8:9], off offset:768
	global_load_dwordx4 v[110:113], v[10:11], off offset:768
	global_load_dwordx4 v[118:121], v[12:13], off offset:768
	global_load_dwordx4 v[122:125], v[14:15], off offset:768
.LBB0_220:
	s_add_i32 s42, s29, -4
	s_cmp_ge_u32 s42, s31
	ds_read_b128 v[204:207], v19
	ds_read_b128 v[208:211], v17 offset:18432
	ds_read_b128 v[212:215], v17 offset:23040
	ds_read_b128 v[216:219], v17 offset:27648
	ds_read_b128 v[220:223], v17 offset:32256
	ds_read_b128 v[224:227], v19 offset:32
	ds_read_b128 v[228:231], v17 offset:18464
	ds_read_b128 v[232:235], v17 offset:23072
	ds_read_b128 v[236:239], v17 offset:27680
	ds_read_b128 v[244:247], v17 offset:32288
	s_waitcnt lgkmcnt(5)
	v_mfma_f32_32x32x16_bf16 a[0:15], v[208:211], v[204:207], a[0:15]
	v_mfma_f32_32x32x16_bf16 a[16:31], v[212:215], v[204:207], a[16:31]
	v_mfma_f32_32x32x16_bf16 a[32:47], v[216:219], v[204:207], a[32:47]
	v_mfma_f32_32x32x16_bf16 a[48:63], v[220:223], v[204:207], a[48:63]
	ds_read_b128 v[204:207], v19 offset:64
	ds_read_b128 v[208:211], v17 offset:18496
	ds_read_b128 v[212:215], v17 offset:23104
	ds_read_b128 v[216:219], v17 offset:27712
	ds_read_b128 v[220:223], v17 offset:32320
	s_waitcnt lgkmcnt(5)
	v_mfma_f32_32x32x16_bf16 a[0:15], v[228:231], v[224:227], a[0:15]
	v_mfma_f32_32x32x16_bf16 a[16:31], v[232:235], v[224:227], a[16:31]
	v_mfma_f32_32x32x16_bf16 a[32:47], v[236:239], v[224:227], a[32:47]
	v_mfma_f32_32x32x16_bf16 a[48:63], v[244:247], v[224:227], a[48:63]
	ds_read_b128 v[224:227], v19 offset:96
	ds_read_b128 v[228:231], v17 offset:18528
	ds_read_b128 v[232:235], v17 offset:23136
	ds_read_b128 v[236:239], v17 offset:27744
	ds_read_b128 v[244:247], v17 offset:32352
	s_waitcnt lgkmcnt(5)
	v_mfma_f32_32x32x16_bf16 a[0:15], v[208:211], v[204:207], a[0:15]
	v_mfma_f32_32x32x16_bf16 a[16:31], v[212:215], v[204:207], a[16:31]
	v_mfma_f32_32x32x16_bf16 a[32:47], v[216:219], v[204:207], a[32:47]
	v_mfma_f32_32x32x16_bf16 a[48:63], v[220:223], v[204:207], a[48:63]
	s_waitcnt lgkmcnt(0)
	v_mfma_f32_32x32x16_bf16 a[0:15], v[228:231], v[224:227], a[0:15]
	v_mfma_f32_32x32x16_bf16 a[16:31], v[232:235], v[224:227], a[16:31]
	v_mfma_f32_32x32x16_bf16 a[32:47], v[236:239], v[224:227], a[32:47]
	v_mfma_f32_32x32x16_bf16 a[48:63], v[244:247], v[224:227], a[48:63]
	s_cbranch_scc1 .LBB0_222
	s_waitcnt vmcnt(24)
	ds_write_b128 v16, v[126:129] offset:36864
	ds_write_b128 v16, v[130:133] offset:55296
	ds_write_b128 v16, v[134:137] offset:41472
	ds_write_b128 v16, v[138:141] offset:59904
	ds_write_b128 v16, v[142:145] offset:46080
	ds_write_b128 v16, v[146:149] offset:64512
	ds_write_b128 v16, v[150:153] offset:50688
	ds_write_b128 v20, v[154:157] offset:55296
.LBB0_222:
	s_cmp_ge_u32 s29, s31
	s_waitcnt lgkmcnt(0)
	s_barrier
	global_load_dwordx4 v[126:129], v[0:1], off offset:896
	global_load_dwordx4 v[130:133], v[2:3], off offset:896
	global_load_dwordx4 v[134:137], v[4:5], off offset:896
	global_load_dwordx4 v[138:141], v[6:7], off offset:896
	global_load_dwordx4 v[142:145], v[8:9], off offset:896
	global_load_dwordx4 v[146:149], v[10:11], off offset:896
	global_load_dwordx4 v[150:153], v[12:13], off offset:896
	global_load_dwordx4 v[154:157], v[14:15], off offset:896
.LBB0_224:
	s_andn2_b64 vcc, exec, s[60:61]
	ds_read_b128 v[204:207], v19 offset:36864
	ds_read_b128 v[208:211], v17 offset:55296
	ds_read_b128 v[212:215], v17 offset:59904
	ds_read_b128 v[216:219], v17 offset:64512
	ds_read_b128 v[220:223], v18 offset:13824
	ds_read_b128 v[224:227], v19 offset:36896
	ds_read_b128 v[228:231], v17 offset:55328
	ds_read_b128 v[232:235], v17 offset:59936
	ds_read_b128 v[236:239], v17 offset:64544
	ds_read_b128 v[244:247], v18 offset:13856
	s_waitcnt lgkmcnt(5)
	v_mfma_f32_32x32x16_bf16 a[0:15], v[208:211], v[204:207], a[0:15]
	v_mfma_f32_32x32x16_bf16 a[16:31], v[212:215], v[204:207], a[16:31]
	v_mfma_f32_32x32x16_bf16 a[32:47], v[216:219], v[204:207], a[32:47]
	v_mfma_f32_32x32x16_bf16 a[48:63], v[220:223], v[204:207], a[48:63]
	ds_read_b128 v[204:207], v19 offset:36928
	ds_read_b128 v[208:211], v17 offset:55360
	ds_read_b128 v[212:215], v17 offset:59968
	ds_read_b128 v[216:219], v17 offset:64576
	ds_read_b128 v[220:223], v18 offset:13888
	s_waitcnt lgkmcnt(5)
	v_mfma_f32_32x32x16_bf16 a[0:15], v[228:231], v[224:227], a[0:15]
	v_mfma_f32_32x32x16_bf16 a[16:31], v[232:235], v[224:227], a[16:31]
	v_mfma_f32_32x32x16_bf16 a[32:47], v[236:239], v[224:227], a[32:47]
	v_mfma_f32_32x32x16_bf16 a[48:63], v[244:247], v[224:227], a[48:63]
	ds_read_b128 v[224:227], v19 offset:36960
	ds_read_b128 v[228:231], v17 offset:55392
	ds_read_b128 v[232:235], v17 offset:60000
	ds_read_b128 v[236:239], v17 offset:64608
	ds_read_b128 v[244:247], v18 offset:13920
	s_waitcnt lgkmcnt(5)
	v_mfma_f32_32x32x16_bf16 a[0:15], v[208:211], v[204:207], a[0:15]
	v_mfma_f32_32x32x16_bf16 a[16:31], v[212:215], v[204:207], a[16:31]
	v_mfma_f32_32x32x16_bf16 a[32:47], v[216:219], v[204:207], a[32:47]
	v_mfma_f32_32x32x16_bf16 a[48:63], v[220:223], v[204:207], a[48:63]
	s_waitcnt lgkmcnt(0)
	v_mfma_f32_32x32x16_bf16 a[0:15], v[228:231], v[224:227], a[0:15]
	v_mfma_f32_32x32x16_bf16 a[16:31], v[232:235], v[224:227], a[16:31]
	v_mfma_f32_32x32x16_bf16 a[32:47], v[236:239], v[224:227], a[32:47]
	v_mfma_f32_32x32x16_bf16 a[48:63], v[244:247], v[224:227], a[48:63]
	s_cbranch_vccnz .LBB0_209
	s_waitcnt vmcnt(24)
	ds_write_b128 v16, v[22:25]
	ds_write_b128 v16, v[26:29] offset:18432
	ds_write_b128 v16, v[30:33] offset:4608
	ds_write_b128 v16, v[34:37] offset:23040
	ds_write_b128 v16, v[38:41] offset:9216
	ds_write_b128 v16, v[42:45] offset:27648
	ds_write_b128 v16, v[46:49] offset:13824
	ds_write_b128 v16, v[54:57] offset:32256
	s_branch .LBB0_209
; DEV uint32_t pk2(float lo, float hi) { f32x2 v; v[0] = lo; v[1] = hi; bf16v2 b = __builtin_convertvector(v, bf16v2); return __builtin_bit_cast(uint32_t, b); }
; template <int EPI>
; DEV void gemm_mini(CParams& p, int layer, const bf16_t* __restrict__ A, int lda, const bf16_t* __restrict__ Bt, int K, int n0, char* lds, const int swave) {
;     ...
;     float* __restrict__ xrow = p.out + (size_t)mc * DM + n0 + 4 * hh;
;     bf16_t* __restrict__ brow = (bf16_t*)(ws + W_XBF) + (size_t)mc * DM + n0 + 4 * hh;
;     f32x4 xv[16];
; #pragma unroll
;     for (int q = 0; q < 16; ++q) xv[q] = *(const f32x4*)(xrow + (q >> 2) * 32 + (q & 3) * 8);
;     float s = 0.f;
; #pragma unroll
;     for (int j = 0; j < 4; ++j)
; #pragma unroll
;       for (int g = 0; g < 4; ++g) {
;         f32x4 v = xv[j * 4 + g];
;         v[0] += acc[j][4 * g]; v[1] += acc[j][4 * g + 1]; v[2] += acc[j][4 * g + 2]; v[3] += acc[j][4 * g + 3];
;         s += v[0] * v[0] + v[1] * v[1] + v[2] * v[2] + v[3] * v[3];
;         *(f32x4*)(xrow + j * 32 + g * 8) = v;
;         u32x2 pk; pk[0] = pk2(v[0], v[1]); pk[1] = pk2(v[2], v[3]);
;         *(u32x2*)(brow + j * 32 + g * 8) = pk;
.LBB0_226:
	s_waitcnt vmcnt(0)
	v_or_b32_e32 v240, s19, v65
	s_waitcnt vmcnt(5)
	v_lshlrev_b64 v[66:67], 12, v[240:241]
	v_lshl_add_u64 v[66:67], s[4:5], 0, v[66:67]
	v_lshl_add_u64 v[66:67], s[82:83], 2, v[66:67]
	v_mov_b32_e32 v65, v241
	s_waitcnt vmcnt(2)
	v_lshl_add_u64 v[112:113], v[66:67], 0, v[64:65]
	v_lshlrev_b64 v[64:65], 11, v[240:241]
	v_lshl_add_u64 v[64:65], s[72:73], 0, v[64:65]
	v_lshl_add_u64 v[134:135], s[82:83], 1, v[64:65]
	global_load_dwordx4 v[118:121], v[112:113], off
	global_load_dwordx4 v[122:125], v[112:113], off offset:32
	global_load_dwordx4 v[126:129], v[112:113], off offset:64
	global_load_dwordx4 v[130:133], v[112:113], off offset:96
	global_load_dwordx4 v[108:111], v[112:113], off offset:128
	global_load_dwordx4 v[104:107], v[112:113], off offset:160
	global_load_dwordx4 v[100:103], v[112:113], off offset:192
	global_load_dwordx4 v[96:99], v[112:113], off offset:224
	global_load_dwordx4 v[92:95], v[112:113], off offset:256
	global_load_dwordx4 v[88:91], v[112:113], off offset:288
	global_load_dwordx4 v[84:87], v[112:113], off offset:320
	global_load_dwordx4 v[80:83], v[112:113], off offset:352
	global_load_dwordx4 v[76:79], v[112:113], off offset:384
	global_load_dwordx4 v[72:75], v[112:113], off offset:416
	global_load_dwordx4 v[68:71], v[112:113], off offset:448
	global_load_dwordx4 v[64:67], v[112:113], off offset:480
	s_waitcnt vmcnt(16)
	v_accvgpr_read_b32 v63, a15
	v_accvgpr_read_b32 v51, a3
	v_accvgpr_read_b32 v50, a2
	v_accvgpr_read_b32 v49, a1
	v_accvgpr_read_b32 v48, a0
	v_lshlrev_b32_e32 v114, 3, v114
	v_mov_b32_e32 v115, v241
	v_accvgpr_read_b32 v55, a7
	v_accvgpr_read_b32 v54, a6
	v_accvgpr_read_b32 v53, a5
	v_accvgpr_read_b32 v52, a4
	v_lshl_add_u64 v[114:115], v[134:135], 0, v[114:115]
	v_accvgpr_read_b32 v59, a11
	v_accvgpr_read_b32 v58, a10
	v_accvgpr_read_b32 v57, a9
	v_accvgpr_read_b32 v56, a8
	v_accvgpr_read_b32 v47, a31
	v_accvgpr_read_b32 v62, a14
	v_accvgpr_read_b32 v61, a13
	v_accvgpr_read_b32 v60, a12
	v_accvgpr_read_b32 v35, a19
	v_accvgpr_read_b32 v34, a18
	v_accvgpr_read_b32 v33, a17
	v_accvgpr_read_b32 v32, a16
	v_accvgpr_read_b32 v39, a23
	v_accvgpr_read_b32 v38, a22
	v_accvgpr_read_b32 v37, a21
	v_accvgpr_read_b32 v36, a20
	v_accvgpr_read_b32 v43, a27
	v_accvgpr_read_b32 v42, a26
	v_accvgpr_read_b32 v41, a25
	v_accvgpr_read_b32 v40, a24
	v_accvgpr_read_b32 v16, a32
	v_accvgpr_read_b32 v46, a30
	v_accvgpr_read_b32 v45, a29
	v_accvgpr_read_b32 v44, a28
	v_accvgpr_read_b32 v17, a33
	v_accvgpr_read_b32 v18, a34
	v_accvgpr_read_b32 v19, a35
	v_accvgpr_read_b32 v20, a36
	v_accvgpr_read_b32 v21, a37
	v_accvgpr_read_b32 v22, a38
	v_accvgpr_read_b32 v23, a39
	v_accvgpr_read_b32 v24, a40
	v_accvgpr_read_b32 v25, a41
	v_accvgpr_read_b32 v26, a42
	v_accvgpr_read_b32 v27, a43
	v_accvgpr_read_b32 v0, a48
	v_accvgpr_read_b32 v28, a44
	v_accvgpr_read_b32 v29, a45
	v_accvgpr_read_b32 v30, a46
	v_accvgpr_read_b32 v31, a47
	v_accvgpr_read_b32 v1, a49
	v_accvgpr_read_b32 v2, a50
	v_accvgpr_read_b32 v3, a51
	v_accvgpr_read_b32 v4, a52
	v_accvgpr_read_b32 v5, a53
	v_accvgpr_read_b32 v14, a62
	v_accvgpr_read_b32 v15, a63
	v_accvgpr_read_b32 v6, a54
	v_accvgpr_read_b32 v7, a55
	v_accvgpr_read_b32 v8, a56
	v_accvgpr_read_b32 v9, a57
	v_accvgpr_read_b32 v10, a58
	s_waitcnt vmcnt(15)
	v_pk_add_f32 v[118:119], v[48:49], v[118:119]
	v_pk_add_f32 v[120:121], v[50:51], v[120:121]
	v_pk_mul_f32 v[50:51], v[118:119], v[118:119]
	global_store_dwordx4 v[112:113], v[118:121], off
	v_pk_mul_f32 v[48:49], v[120:121], v[120:121]
	s_waitcnt vmcnt(12)
	v_pk_add_f32 v[108:109], v[32:33], v[108:109]
	v_cvt_pk_bf16_f32 v118, v118, v119
	v_cvt_pk_bf16_f32 v119, v120, v121
	global_store_dwordx2 v[114:115], v[118:119], off
	v_pk_add_f32 v[118:119], v[52:53], v[122:123]
	v_pk_add_f32 v[120:121], v[54:55], v[124:125]
	v_pk_mul_f32 v[54:55], v[118:119], v[118:119]
	global_store_dwordx4 v[112:113], v[118:121], off offset:32
	v_pk_mul_f32 v[52:53], v[120:121], v[120:121]
	v_pk_add_f32 v[110:111], v[34:35], v[110:111]
	v_cvt_pk_bf16_f32 v118, v118, v119
	v_cvt_pk_bf16_f32 v119, v120, v121
	global_store_dwordx2 v[114:115], v[118:119], off offset:16
	v_pk_add_f32 v[118:119], v[56:57], v[126:127]
	v_pk_add_f32 v[120:121], v[58:59], v[128:129]
	v_pk_mul_f32 v[58:59], v[118:119], v[118:119]
	global_store_dwordx4 v[112:113], v[118:121], off offset:64
	v_pk_mul_f32 v[56:57], v[120:121], v[120:121]
	v_pk_mul_f32 v[34:35], v[108:109], v[108:109]
	v_cvt_pk_bf16_f32 v118, v118, v119
	v_cvt_pk_bf16_f32 v119, v120, v121
	global_store_dwordx2 v[114:115], v[118:119], off offset:32
	v_pk_add_f32 v[118:119], v[60:61], v[130:131]
	v_pk_add_f32 v[120:121], v[62:63], v[132:133]
	v_pk_mul_f32 v[62:63], v[118:119], v[118:119]
	global_store_dwordx4 v[112:113], v[118:121], off offset:96
	s_waitcnt vmcnt(17)
	v_pk_add_f32 v[104:105], v[36:37], v[104:105]
	v_pk_add_f32 v[106:107], v[38:39], v[106:107]
	v_cvt_pk_bf16_f32 v118, v118, v119
	v_cvt_pk_bf16_f32 v119, v120, v121
	global_store_dwordx2 v[114:115], v[118:119], off offset:48
	global_store_dwordx4 v[112:113], v[108:111], off offset:128
	v_pk_mul_f32 v[38:39], v[104:105], v[104:105]
	s_waitcnt vmcnt(18)
	v_pk_add_f32 v[40:41], v[40:41], v[100:101]
	v_cvt_pk_bf16_f32 v108, v108, v109
	v_cvt_pk_bf16_f32 v109, v110, v111
	global_store_dwordx2 v[114:115], v[108:109], off offset:64
	global_store_dwordx4 v[112:113], v[104:107], off offset:160
	v_pk_add_f32 v[42:43], v[42:43], v[102:103]
	v_pk_mul_f32 v[100:101], v[40:41], v[40:41]
	v_cvt_pk_bf16_f32 v104, v104, v105
	v_cvt_pk_bf16_f32 v105, v106, v107
	global_store_dwordx2 v[114:115], v[104:105], off offset:80
	global_store_dwordx4 v[112:113], v[40:43], off offset:192
	v_pk_mul_f32 v[102:103], v[42:43], v[42:43]
	s_waitcnt vmcnt(20)
; DEV uint32_t pk2(float lo, float hi) { f32x2 v; v[0] = lo; v[1] = hi; bf16v2 b = __builtin_convertvector(v, bf16v2); return __builtin_bit_cast(uint32_t, b); }
; DEV float shx(float v, int o, int lane) { return __builtin_bit_cast(float, __builtin_amdgcn_ds_bpermute((lane ^ o) << 2, __builtin_bit_cast(int, v))); }
; template <int EPI>
; DEV void gemm_mini(CParams& p, int layer, const bf16_t* __restrict__ A, int lda, const bf16_t* __restrict__ Bt, int K, int n0, char* lds, const int swave) {
;     ...
; #pragma unroll
;     for (int j = 0; j < 4; ++j)
; #pragma unroll
;       for (int g = 0; g < 4; ++g) {
;         f32x4 v = xv[j * 4 + g];
;         v[0] += acc[j][4 * g]; v[1] += acc[j][4 * g + 1]; v[2] += acc[j][4 * g + 2]; v[3] += acc[j][4 * g + 3];
;         s += v[0] * v[0] + v[1] * v[1] + v[2] * v[2] + v[3] * v[3];
;         *(f32x4*)(xrow + j * 32 + g * 8) = v;
;         u32x2 pk; pk[0] = pk2(v[0], v[1]); pk[1] = pk2(v[2], v[3]);
;         *(u32x2*)(brow + j * 32 + g * 8) = pk;
;       }
;     s += shx(s, 32, lane);
;     if (hh == 0) ((float*)(ws + W_SSQ))[(size_t)mc * NPART + (n0 >> 7)] = s;
	v_pk_add_f32 v[16:17], v[16:17], v[92:93]
	v_cvt_pk_bf16_f32 v40, v40, v41
	v_cvt_pk_bf16_f32 v41, v42, v43
	global_store_dwordx2 v[114:115], v[40:41], off offset:96
	v_pk_add_f32 v[40:41], v[44:45], v[96:97]
	v_pk_add_f32 v[42:43], v[46:47], v[98:99]
	v_pk_mul_f32 v[44:45], v[40:41], v[40:41]
	global_store_dwordx4 v[112:113], v[40:43], off offset:224
	v_pk_add_f32 v[18:19], v[18:19], v[94:95]
	v_pk_mul_f32 v[46:47], v[42:43], v[42:43]
	v_cvt_pk_bf16_f32 v40, v40, v41
	v_cvt_pk_bf16_f32 v41, v42, v43
	global_store_dwordx2 v[114:115], v[40:41], off offset:112
	v_pk_mul_f32 v[40:41], v[16:17], v[16:17]
	global_store_dwordx4 v[112:113], v[16:19], off offset:256
	v_pk_mul_f32 v[42:43], v[18:19], v[18:19]
	s_waitcnt vmcnt(20)
	v_pk_add_f32 v[0:1], v[0:1], v[76:77]
	v_cvt_pk_bf16_f32 v16, v16, v17
	v_cvt_pk_bf16_f32 v17, v18, v19
	global_store_dwordx2 v[114:115], v[16:17], off offset:128
	v_pk_add_f32 v[16:17], v[20:21], v[88:89]
	v_pk_add_f32 v[18:19], v[22:23], v[90:91]
	v_pk_mul_f32 v[20:21], v[16:17], v[16:17]
	global_store_dwordx4 v[112:113], v[16:19], off offset:288
	v_pk_mul_f32 v[22:23], v[18:19], v[18:19]
	v_pk_add_f32 v[2:3], v[2:3], v[78:79]
	v_cvt_pk_bf16_f32 v16, v16, v17
	v_cvt_pk_bf16_f32 v17, v18, v19
	global_store_dwordx2 v[114:115], v[16:17], off offset:144
	v_pk_add_f32 v[16:17], v[24:25], v[84:85]
	v_pk_add_f32 v[18:19], v[26:27], v[86:87]
	v_pk_mul_f32 v[24:25], v[16:17], v[16:17]
	global_store_dwordx4 v[112:113], v[16:19], off offset:320
	v_pk_mul_f32 v[26:27], v[18:19], v[18:19]
	v_pk_mul_f32 v[60:61], v[120:121], v[120:121]
	v_cvt_pk_bf16_f32 v16, v16, v17
	v_cvt_pk_bf16_f32 v17, v18, v19
	global_store_dwordx2 v[114:115], v[16:17], off offset:160
	v_pk_add_f32 v[16:17], v[28:29], v[80:81]
	v_pk_add_f32 v[18:19], v[30:31], v[82:83]
	v_pk_mul_f32 v[28:29], v[16:17], v[16:17]
	global_store_dwordx4 v[112:113], v[16:19], off offset:352
	v_pk_mul_f32 v[32:33], v[110:111], v[110:111]
	v_pk_mul_f32 v[36:37], v[106:107], v[106:107]
	v_cvt_pk_bf16_f32 v16, v16, v17
	v_cvt_pk_bf16_f32 v17, v18, v19
	global_store_dwordx2 v[114:115], v[16:17], off offset:176
	v_pk_mul_f32 v[16:17], v[0:1], v[0:1]
	global_store_dwordx4 v[112:113], v[0:3], off offset:384
	v_pk_mul_f32 v[30:31], v[18:19], v[18:19]
	v_pk_mul_f32 v[18:19], v[2:3], v[2:3]
	v_cvt_pk_bf16_f32 v0, v0, v1
	v_cvt_pk_bf16_f32 v1, v2, v3
	global_store_dwordx2 v[114:115], v[0:1], off offset:192
	s_waitcnt vmcnt(28)
	v_pk_add_f32 v[0:1], v[4:5], v[72:73]
	s_waitcnt vmcnt(26)
	v_pk_add_f32 v[4:5], v[14:15], v[66:67]
	v_add_f32_e32 v14, v54, v55
	v_add_f32_e32 v15, v50, v51
	v_add_f32_e32 v14, v52, v14
	v_add_f32_e32 v15, v48, v15
	v_add_f32_e32 v14, v53, v14
	v_add_f32_e32 v15, v49, v15
	v_add_f32_e32 v14, v15, v14
	v_add_f32_e32 v15, v58, v59
	v_add_f32_e32 v15, v56, v15
	v_add_f32_e32 v15, v57, v15
	v_add_f32_e32 v14, v14, v15
	v_add_f32_e32 v15, v62, v63
	v_add_f32_e32 v15, v60, v15
	v_add_f32_e32 v15, v61, v15
	v_add_f32_e32 v14, v14, v15
	v_add_f32_e32 v15, v34, v35
	v_add_f32_e32 v15, v32, v15
	v_add_f32_e32 v15, v33, v15
	v_add_f32_e32 v14, v14, v15
	v_add_f32_e32 v15, v38, v39
	v_add_f32_e32 v15, v36, v15
	v_add_f32_e32 v15, v37, v15
	v_add_f32_e32 v14, v14, v15
	v_add_f32_e32 v15, v100, v101
	v_add_f32_e32 v15, v102, v15
	v_add_f32_e32 v15, v103, v15
	v_add_f32_e32 v14, v14, v15
	v_add_f32_e32 v15, v44, v45
	v_add_f32_e32 v15, v46, v15
	v_add_f32_e32 v15, v47, v15
	v_add_f32_e32 v14, v14, v15
	v_add_f32_e32 v15, v40, v41
	v_add_f32_e32 v15, v42, v15
	v_add_f32_e32 v15, v43, v15
	v_add_f32_e32 v14, v14, v15
	v_add_f32_e32 v15, v20, v21
	v_add_f32_e32 v15, v22, v15
	v_add_f32_e32 v15, v23, v15
	v_add_f32_e32 v14, v14, v15
	v_add_f32_e32 v15, v24, v25
	v_add_f32_e32 v15, v26, v15
	v_add_f32_e32 v15, v27, v15
	v_add_f32_e32 v14, v14, v15
	v_add_f32_e32 v15, v28, v29
	v_pk_add_f32 v[2:3], v[6:7], v[74:75]
	v_add_f32_e32 v15, v30, v15
	v_accvgpr_read_b32 v11, a59
	v_pk_mul_f32 v[6:7], v[0:1], v[0:1]
	global_store_dwordx4 v[112:113], v[0:3], off offset:416
	v_add_f32_e32 v15, v31, v15
	v_accvgpr_read_b32 v12, a60
	v_cvt_pk_bf16_f32 v0, v0, v1
	v_cvt_pk_bf16_f32 v1, v2, v3
	v_accvgpr_read_b32 v13, a61
	v_pk_mul_f32 v[72:73], v[2:3], v[2:3]
	global_store_dwordx2 v[114:115], v[0:1], off offset:208
	v_pk_add_f32 v[0:1], v[8:9], v[68:69]
	v_pk_add_f32 v[2:3], v[10:11], v[70:71]
	v_add_f32_e32 v14, v14, v15
	v_add_f32_e32 v15, v16, v17
	v_pk_mul_f32 v[8:9], v[0:1], v[0:1]
	v_pk_mul_f32 v[10:11], v[2:3], v[2:3]
	global_store_dwordx4 v[112:113], v[0:3], off offset:448
	v_add_f32_e32 v15, v18, v15
	v_add_f32_e32 v6, v6, v7
	v_cvt_pk_bf16_f32 v0, v0, v1
	v_cvt_pk_bf16_f32 v1, v2, v3
	v_pk_add_f32 v[2:3], v[12:13], v[64:65]
	global_store_dwordx2 v[114:115], v[0:1], off offset:224
	v_pk_mul_f32 v[0:1], v[2:3], v[2:3]
	v_add_f32_e32 v15, v19, v15
	v_add_f32_e32 v6, v72, v6
	v_add_f32_e32 v7, v8, v9
	v_pk_mul_f32 v[12:13], v[4:5], v[4:5]
	v_add_f32_e32 v14, v14, v15
	v_add_f32_e32 v6, v73, v6
	v_add_f32_e32 v7, v10, v7
	v_add_f32_e32 v0, v0, v1
	v_add_f32_e32 v6, v14, v6
	v_add_f32_e32 v7, v11, v7
	v_add_f32_e32 v0, v12, v0
	v_add_f32_e32 v6, v6, v7
	v_add_f32_e32 v0, v13, v0
	v_lshlrev_b32_e32 v1, 2, v116
	v_add_f32_e32 v0, v6, v0
	v_xor_b32_e32 v1, 0x80, v1
	ds_bpermute_b32 v1, v1, v0
	global_store_dwordx4 v[112:113], v[2:5], off offset:480
	v_cmp_gt_u32_e32 vcc, 32, v116
	s_nop 0
	v_cvt_pk_bf16_f32 v2, v2, v3
	v_cvt_pk_bf16_f32 v3, v4, v5
	global_store_dwordx2 v[114:115], v[2:3], off offset:240
	s_and_saveexec_b64 s[6:7], vcc
	s_cbranch_execz .LBB0_207
	v_lshlrev_b64 v[2:3], 5, v[240:241]
	v_lshl_add_u64 v[2:3], s[74:75], 0, v[2:3]
	s_ashr_i32 s81, s80, 31
	v_lshl_add_u64 v[2:3], s[80:81], 2, v[2:3]
	s_waitcnt lgkmcnt(0)
	v_add_f32_e32 v0, v0, v1
	global_store_dword v[2:3], v0, off
	s_branch .LBB0_207

; DEV uint32_t pk2(float lo, float hi) { f32x2 v; v[0] = lo; v[1] = hi; bf16v2 b = __builtin_convertvector(v, bf16v2); return __builtin_bit_cast(uint32_t, b); }
; DEV f32x16 mfma32(bf16x8 a, bf16x8 b, f32x16 c) { return __builtin_amdgcn_mfma_f32_32x32x16_bf16(a, b, c, 0, 0, 0); }
; template <bool SAMPLE>
; DEV void attn_unit(CParams& p, int layer, int unit, float lam, float lam_init, char* lds, const int swave) {
;     ...
;   for (int t = 0; t < ntiles; ++t) {
;     const int tn = SAMPLE ? t + 1 : (t + 1 < ntiles ? t + 1 : t);
;     if (!SAMPLE || t + 1 < ntiles) gloadK(tn);
;     if (t < my_tiles) {
;       const char* Ks = lds + (t & 1) * A_BUF; const char* Vs = Ks + A_KT;
;       bf16x8 pf[2][4];
;       f32x16 S0, S1;
;       auto qk = [&](int br) {
;         const f32x16 zc = {0.f, 0.f, 0.f, 0.f, 0.f, 0.f, 0.f, 0.f, 0.f, 0.f, 0.f, 0.f, 0.f, 0.f, 0.f, 0.f};
; #pragma unroll
;         for (int ks = 0; ks < 4; ++ks) {
;           const bf16x8 k0 = lds_read8(Ks + lr * AK_B + (br * 64 + ks * 16 + hh * 8) * 2);
;           const bf16x8 k1 = lds_read8(Ks + (32 + lr) * AK_B + (br * 64 + ks * 16 + hh * 8) * 2);
;           S0 = mfma32(k0, qf[br][ks], ks == 0 ? zc : S0); S1 = mfma32(k1, qf[br][ks], ks == 0 ? zc : S1);
;         }
;         if (sample && t == 32) {
; #pragma unroll
;           for (int r = 0; r < 16; ++r) { if (r >= 8) S0[r] = -1e30f; S1[r] = -1e30f; }
;         }
;       };
;       auto sm8 = [&](const f32x16& Sx, int r0, float nm, float& lsum) -> bf16x8 {
;         f32x2 c2; c2[0] = cexp; c2[1] = cexp;
;         f32x2 nm2; nm2[0] = nm; nm2[1] = nm;
;         union { u32x4 u; bf16x8 b; } x;
;         f32x2 sum2; sum2[0] = 0.f; sum2[1] = 0.f;
; #pragma unroll
;         for (int r = 0; r < 8; r += 2) {
;           f32x2 v; v[0] = Sx[r0 + r]; v[1] = Sx[r0 + r + 1];
;           v = v * c2 + nm2;
;           f32x2 ex; ex[0] = __builtin_amdgcn_exp2f(v[0]); ex[1] = __builtin_amdgcn_exp2f(v[1]);
;           sum2 += ex;
;           x.u[r >> 1] = pk2(ex[0], ex[1]);
;         }
;         lsum += sum2[0] + sum2[1];
;         return x.b;
;       };
;       qk(0);
;       pf[0][0] = sm8(S0, 0, nmc[0], ls[0]); pf[0][1] = sm8(S0, 8, nmc[0], ls[0]);
;       pf[0][2] = sm8(S1, 0, nmc[0], ls[0]); pf[0][3] = sm8(S1, 8, nmc[0], ls[0]);
;       qk(1);
;       if (!SAMPLE || t + 1 < ntiles) gloadV(tn);
.LBB0_243:
	s_add_i32 s36, s37, 1
	s_cmp_ge_u32 s36, s23
	s_cselect_b64 s[6:7], -1, 0
	s_cmp_lt_u32 s36, s23
	s_cselect_b32 s8, s36, s37
	s_lshl_b32 s38, s8, 6
	s_add_i32 s8, s38, s28
	s_mul_hi_i32 s9, s8, 0xc00
	s_mulk_i32 s8, 0xc00
	s_or_b64 s[8:9], s[8:9], s[2:3]
	v_lshl_add_u64 v[54:55], s[8:9], 1, v[50:51]
	s_add_i32 s8, s30, s38
	s_mul_hi_i32 s9, s8, 0xc00
	s_mulk_i32 s8, 0xc00
	s_or_b64 s[8:9], s[8:9], s[2:3]
	v_lshl_add_u64 v[56:57], s[8:9], 1, v[50:51]
	s_add_i32 s8, s31, s38
	s_mul_hi_i32 s9, s8, 0xc00
	s_mulk_i32 s8, 0xc00
	s_or_b64 s[8:9], s[8:9], s[2:3]
	v_lshl_add_u64 v[58:59], s[8:9], 1, v[50:51]
	s_add_i32 s8, s34, s38
	s_mul_hi_i32 s9, s8, 0xc00
	s_mulk_i32 s8, 0xc00
	s_or_b64 s[8:9], s[8:9], s[2:3]
	global_load_dwordx4 v[4:7], v[54:55], off
	global_load_dwordx4 v[0:3], v[56:57], off
	v_lshl_add_u64 v[60:61], s[8:9], 1, v[50:51]
	global_load_dwordx4 v[12:15], v[58:59], off
	global_load_dwordx4 v[8:11], v[60:61], off
	global_load_dwordx4 v[194:197], v[54:55], off offset:1024
	global_load_dwordx4 v[198:201], v[56:57], off offset:1024
	global_load_dwordx4 v[202:205], v[58:59], off offset:1024
	global_load_dwordx4 v[206:209], v[60:61], off offset:1024
	s_cmp_ge_u32 s37, s29
	s_cselect_b64 s[8:9], -1, 0
	s_and_b64 vcc, exec, s[8:9]
	s_cbranch_vccnz .LBB0_245
	s_bitcmp1_b32 s37, 0
	s_cselect_b32 s38, 0x9400, 0
	s_add_i32 s38, s38, 16
	v_add3_u32 v118, s38, v85, v240
	ds_read_b128 v[62:65], v118
	ds_read_b128 v[66:69], v118 offset:32
	s_waitcnt lgkmcnt(1)
	v_mfma_f32_32x32x16_bf16 a[176:191], v[62:65], v[16:19], 0
	ds_read_b128 v[62:65], v118 offset:8704
	ds_read_b128 v[70:73], v118 offset:8736
	s_waitcnt lgkmcnt(1)
	v_mfma_f32_32x32x16_bf16 a[160:175], v[62:65], v[16:19], 0
	v_mfma_f32_32x32x16_bf16 a[176:191], v[66:69], v[20:23], a[176:191]
	ds_read_b128 v[62:65], v118 offset:64
	ds_read_b128 v[66:69], v118 offset:96
	s_waitcnt lgkmcnt(2)
	v_mfma_f32_32x32x16_bf16 a[160:175], v[70:73], v[20:23], a[160:175]
	s_waitcnt lgkmcnt(1)
	v_mfma_f32_32x32x16_bf16 a[176:191], v[62:65], v[24:27], a[176:191]
	ds_read_b128 v[62:65], v118 offset:8768
	ds_read_b128 v[70:73], v118 offset:8800
	ds_read_b128 v[88:91], v118 offset:128
	s_waitcnt lgkmcnt(2)
	v_mfma_f32_32x32x16_bf16 a[160:175], v[62:65], v[24:27], a[160:175]
	s_waitcnt lgkmcnt(0)
	v_mfma_f32_32x32x16_bf16 a[144:159], v[88:91], v[32:35], 0
	v_mfma_f32_32x32x16_bf16 a[176:191], v[66:69], v[28:31], a[176:191]
	v_mfma_f32_32x32x16_bf16 a[160:175], v[70:73], v[28:31], a[160:175]
	ds_read_b128 v[68:71], v118 offset:8832
	ds_read_b128 v[92:95], v118 offset:160
	ds_read_b128 v[88:91], v118 offset:8864
	s_nop 7
	v_accvgpr_read_b32 v97, a179
	v_accvgpr_read_b32 v96, a178
	v_pk_fma_f32 v[102:103], v[96:97], s[52:53], v[48:49] op_sel_hi:[1,0,1]
	v_accvgpr_read_b32 v109, a181
	s_waitcnt lgkmcnt(2)
	v_mfma_f32_32x32x16_bf16 a[128:143], v[68:71], v[32:35], 0
	v_accvgpr_read_b32 v108, a180
	v_accvgpr_read_b32 v63, a183
	v_accvgpr_read_b32 v62, a182
	v_fma_f32 v62, v62, s52, v48
	v_fma_f32 v63, v63, s52, v49
	v_accvgpr_read_b32 v107, a185
	v_accvgpr_read_b32 v106, a184
	v_accvgpr_read_b32 v105, a187
	s_waitcnt lgkmcnt(1)
	v_mfma_f32_32x32x16_bf16 a[144:159], v[92:95], v[36:39], a[144:159]
	ds_read_b128 v[92:95], v118 offset:192
	v_accvgpr_read_b32 v104, a186
	v_accvgpr_read_b32 v67, a189
	v_accvgpr_read_b32 v66, a188
	v_fma_f32 v66, v66, s52, v48
	v_fma_f32 v67, v67, s52, v49
	v_accvgpr_read_b32 v65, a191
	v_exp_f32_e32 v66, v66
	s_waitcnt lgkmcnt(1)
	v_mfma_f32_32x32x16_bf16 a[128:143], v[88:91], v[36:39], a[128:143]
	v_accvgpr_read_b32 v88, a176
	v_accvgpr_read_b32 v89, a177
	v_fma_f32 v88, v88, s52, v48
	v_fma_f32 v89, v89, s52, v49
	v_exp_f32_e32 v67, v67
	v_exp_f32_e32 v100, v88
	v_exp_f32_e32 v101, v89
	ds_read_b128 v[88:91], v118 offset:8896
	ds_read_b128 v[96:99], v118 offset:224
	s_waitcnt lgkmcnt(2)
	v_mfma_f32_32x32x16_bf16 a[144:159], v[92:95], v[40:43], a[144:159]
	v_exp_f32_e32 v94, v102
	v_exp_f32_e32 v95, v103
	v_pk_add_f32 v[102:103], v[100:101], 0 op_sel_hi:[1,0]
	v_cvt_pk_bf16_f32 v92, v100, v101
	v_accvgpr_read_b32 v64, a190
	v_pk_add_f32 v[116:117], v[94:95], v[102:103]
	ds_read_b128 v[100:103], v118 offset:8928
	s_waitcnt lgkmcnt(2)
	v_mfma_f32_32x32x16_bf16 a[128:143], v[88:91], v[40:43], a[128:143]
	v_fma_f32 v88, v108, s52, v48
	v_fma_f32 v89, v109, s52, v49
	v_exp_f32_e32 v90, v62
	v_exp_f32_e32 v88, v88
	v_exp_f32_e32 v89, v89
	v_exp_f32_e32 v91, v63
	v_add3_u32 v108, s38, v87, v86
	v_cvt_pk_bf16_f32 v93, v94, v95
	v_pk_add_f32 v[62:63], v[88:89], v[116:117]
	v_cvt_pk_bf16_f32 v94, v88, v89
	ds_read_b64_tr_b16 v[116:117], v108 offset:17408
	ds_read_b64_tr_b16 v[118:119], v108 offset:19968
	s_waitcnt lgkmcnt(2)
	v_mfma_f32_32x32x16_bf16 a[128:143], v[100:103], v[44:47], a[128:143]
	v_fma_f32 v88, v106, s52, v48
	v_fma_f32 v89, v107, s52, v49
	ds_read_b64_tr_b16 v[100:101], v108 offset:17472
	ds_read_b64_tr_b16 v[122:123], v108 offset:17536
	ds_read_b64_tr_b16 v[142:143], v108 offset:17600
	ds_read_b64_tr_b16 v[102:103], v108 offset:20032
	ds_read_b64_tr_b16 v[124:125], v108 offset:20096
	ds_read_b64_tr_b16 v[144:145], v108 offset:20160
	v_pk_add_f32 v[62:63], v[90:91], v[62:63]
	v_cvt_pk_bf16_f32 v95, v90, v91
	v_exp_f32_e32 v88, v88
	v_exp_f32_e32 v89, v89
	v_pk_fma_f32 v[90:91], v[104:105], s[52:53], v[48:49] op_sel_hi:[1,0,1]
	v_mfma_f32_32x32x16_bf16 a[144:159], v[96:99], v[44:47], a[144:159]
	v_exp_f32_e32 v90, v90
	v_exp_f32_e32 v91, v91
	v_pk_add_f32 v[96:97], v[88:89], 0 op_sel_hi:[1,0]
	v_pk_fma_f32 v[64:65], v[64:65], s[52:53], v[48:49] op_sel_hi:[1,0,1]
	v_cvt_pk_bf16_f32 v88, v88, v89
	v_pk_add_f32 v[96:97], v[90:91], v[96:97]
	v_exp_f32_e32 v98, v64
	s_waitcnt lgkmcnt(6)
; DEV uint32_t pk2(float lo, float hi) { f32x2 v; v[0] = lo; v[1] = hi; bf16v2 b = __builtin_convertvector(v, bf16v2); return __builtin_bit_cast(uint32_t, b); }
; DEV f32x16 mfma32(bf16x8 a, bf16x8 b, f32x16 c) { return __builtin_amdgcn_mfma_f32_32x32x16_bf16(a, b, c, 0, 0, 0); }
; template <bool SAMPLE>
; DEV void attn_unit(CParams& p, int layer, int unit, float lam, float lam_init, char* lds, const int swave) {
;     ...
;       auto sm8 = [&](const f32x16& Sx, int r0, float nm, float& lsum) -> bf16x8 {
;         f32x2 c2; c2[0] = cexp; c2[1] = cexp;
;         f32x2 nm2; nm2[0] = nm; nm2[1] = nm;
;         union { u32x4 u; bf16x8 b; } x;
;         f32x2 sum2; sum2[0] = 0.f; sum2[1] = 0.f;
; #pragma unroll
;         for (int r = 0; r < 8; r += 2) {
;           f32x2 v; v[0] = Sx[r0 + r]; v[1] = Sx[r0 + r + 1];
;           v = v * c2 + nm2;
;           f32x2 ex; ex[0] = __builtin_amdgcn_exp2f(v[0]); ex[1] = __builtin_amdgcn_exp2f(v[1]);
;           sum2 += ex;
;           x.u[r >> 1] = pk2(ex[0], ex[1]);
;         }
;         lsum += sum2[0] + sum2[1];
;         return x.b;
;       };
;       qk(0);
;       pf[0][0] = sm8(S0, 0, nmc[0], ls[0]); pf[0][1] = sm8(S0, 8, nmc[0], ls[0]);
;       pf[0][2] = sm8(S1, 0, nmc[0], ls[0]); pf[0][3] = sm8(S1, 8, nmc[0], ls[0]);
;       qk(1);
;       if (!SAMPLE || t + 1 < ntiles) gloadV(tn);
; #pragma unroll
;       for (int sl = 0; sl < 4; ++sl) {
; #pragma unroll
;         for (int e = 0; e < 4; ++e) {
;           const bf16x8 vf = tr8(Vs, AV_B, sl * 16, e * 32, lane);
;           O1[e] = mfma32(vf, pf[0][sl], O1[e]);
;         }
;         pf[1][sl] = sm8(sl < 2 ? S0 : S1, (sl & 1) * 8, nmc[1], ls[1]);
;       }
	v_mfma_f32_32x32x16_bf16 a[0:15], v[116:119], v[92:95], a[0:15]
	v_exp_f32_e32 v99, v65
	v_cvt_pk_bf16_f32 v89, v90, v91
	v_pk_add_f32 v[64:65], v[66:67], v[96:97]
	v_cvt_pk_bf16_f32 v90, v66, v67
	v_accvgpr_read_b32 v66, a160
	ds_read_b64_tr_b16 v[146:147], v108 offset:22528
	ds_read_b64_tr_b16 v[148:149], v108 offset:25088
	v_accvgpr_read_b32 v67, a161
	s_waitcnt lgkmcnt(4)
	v_mfma_f32_32x32x16_bf16 a[32:47], v[100:103], v[92:95], a[32:47]
	ds_read_b64_tr_b16 v[150:151], v108 offset:22592
	ds_read_b64_tr_b16 v[154:155], v108 offset:22656
	ds_read_b64_tr_b16 v[158:159], v108 offset:22720
	ds_read_b64_tr_b16 v[152:153], v108 offset:25152
	ds_read_b64_tr_b16 v[156:157], v108 offset:25216
	ds_read_b64_tr_b16 v[160:161], v108 offset:25280
	v_accvgpr_read_b32 v115, a163
	v_accvgpr_read_b32 v114, a162
	v_pk_fma_f32 v[66:67], v[66:67], s[52:53], v[48:49] op_sel_hi:[1,0,1]
	v_cvt_pk_bf16_f32 v91, v98, v99
	v_exp_f32_e32 v66, v66
	v_exp_f32_e32 v67, v67
	s_waitcnt lgkmcnt(9)
	v_mfma_f32_32x32x16_bf16 a[64:79], v[122:125], v[92:95], a[64:79]
	v_accvgpr_read_b32 v111, a167
	v_accvgpr_read_b32 v110, a166
	v_accvgpr_read_b32 v113, a165
	v_accvgpr_read_b32 v112, a164
	v_add_f32_e64 v96, v66, 0
	v_add_f32_e64 v97, v67, 0
	v_pk_add_f32 v[64:65], v[98:99], v[64:65]
	v_pk_fma_f32 v[98:99], v[110:111], s[52:53], v[48:49] op_sel_hi:[1,0,1]
	s_waitcnt lgkmcnt(8)
	v_mfma_f32_32x32x16_bf16 a[96:111], v[142:145], v[92:95], a[96:111]
	v_fma_f32 v92, v114, s52, v48
	v_fma_f32 v93, v115, s52, v49
	v_exp_f32_e32 v98, v98
	v_exp_f32_e32 v94, v92
	v_exp_f32_e32 v95, v93
	v_cvt_pk_bf16_f32 v92, v66, v67
	v_exp_f32_e32 v99, v99
	ds_read_b64_tr_b16 v[162:163], v108 offset:27648
	ds_read_b64_tr_b16 v[164:165], v108 offset:30208
	s_waitcnt lgkmcnt(8)
	v_mfma_f32_32x32x16_bf16 a[0:15], v[146:149], v[88:91], a[0:15]
	v_add_f32_e64 v66, v94, v96
	v_add_f32_e64 v67, v95, v97
	v_fma_f32 v96, v112, s52, v48
	v_fma_f32 v97, v113, s52, v49
	ds_read_b64_tr_b16 v[166:167], v108 offset:27712
	ds_read_b64_tr_b16 v[170:171], v108 offset:27776
	ds_read_b64_tr_b16 v[174:175], v108 offset:27840
	ds_read_b64_tr_b16 v[168:169], v108 offset:30272
	ds_read_b64_tr_b16 v[172:173], v108 offset:30336
	ds_read_b64_tr_b16 v[176:177], v108 offset:30400
	v_exp_f32_e32 v96, v96
	v_exp_f32_e32 v97, v97
	v_accvgpr_read_b32 v75, a169
	v_accvgpr_read_b32 v74, a168
	s_waitcnt lgkmcnt(10)
	v_mfma_f32_32x32x16_bf16 a[32:47], v[150:153], v[88:91], a[32:47]
	v_accvgpr_read_b32 v73, a171
	v_accvgpr_read_b32 v72, a170
	v_fma_f32 v74, v74, s52, v48
	v_fma_f32 v75, v75, s52, v49
	v_fma_f32 v72, v72, s52, v48
	v_fma_f32 v73, v73, s52, v49
	v_exp_f32_e32 v74, v74
	v_exp_f32_e32 v75, v75
	v_cvt_pk_bf16_f32 v93, v94, v95
	s_waitcnt lgkmcnt(9)
	v_mfma_f32_32x32x16_bf16 a[64:79], v[154:157], v[88:91], a[64:79]
	v_cvt_pk_bf16_f32 v94, v96, v97
	v_cvt_pk_bf16_f32 v95, v98, v99
	v_accvgpr_read_b32 v71, a173
	v_accvgpr_read_b32 v70, a172
	v_accvgpr_read_b32 v69, a175
	v_accvgpr_read_b32 v68, a174
	v_pk_fma_f32 v[70:71], v[70:71], s[52:53], v[48:49] op_sel_hi:[1,0,1]
	s_waitcnt lgkmcnt(8)
	v_mfma_f32_32x32x16_bf16 a[96:111], v[158:161], v[88:91], a[96:111]
	v_exp_f32_e32 v88, v72
	v_exp_f32_e32 v89, v73
	v_pk_add_f32 v[90:91], v[74:75], 0 op_sel_hi:[1,0]
	v_exp_f32_e32 v70, v70
	v_exp_f32_e32 v71, v71
	v_pk_fma_f32 v[68:69], v[68:69], s[52:53], v[48:49] op_sel_hi:[1,0,1]
	v_cvt_pk_bf16_f32 v72, v74, v75
	s_waitcnt lgkmcnt(6)
	v_mfma_f32_32x32x16_bf16 a[0:15], v[162:165], v[92:95], a[0:15]
	v_add_f32_e64 v74, v88, v90
	v_add_f32_e64 v75, v89, v91
	v_exp_f32_e32 v90, v68
	v_exp_f32_e32 v91, v69
	ds_read_b64_tr_b16 v[178:179], v108 offset:32768
	ds_read_b64_tr_b16 v[180:181], v108 offset:35328
	ds_read_b64_tr_b16 v[182:183], v108 offset:32832
	ds_read_b64_tr_b16 v[186:187], v108 offset:32896
	ds_read_b64_tr_b16 v[190:191], v108 offset:32960
	ds_read_b64_tr_b16 v[184:185], v108 offset:35392
	ds_read_b64_tr_b16 v[188:189], v108 offset:35456
	ds_read_b64_tr_b16 v[192:193], v108 offset:35520
	v_pk_add_f32 v[66:67], v[96:97], v[66:67]
	v_pk_add_f32 v[68:69], v[70:71], v[74:75]
	s_waitcnt lgkmcnt(10)
	v_mfma_f32_32x32x16_bf16 a[32:47], v[166:169], v[92:95], a[32:47]
	v_add_f32_e64 v66, v98, v66
	v_add_f32_e64 v67, v99, v67
	v_accvgpr_read_b32 v98, a144
	v_cvt_pk_bf16_f32 v74, v70, v71
	v_accvgpr_read_b32 v71, a151
	v_accvgpr_read_b32 v70, a150
	v_accvgpr_read_b32 v97, a147
	v_accvgpr_read_b32 v96, a146
	s_waitcnt lgkmcnt(9)
	v_mfma_f32_32x32x16_bf16 a[64:79], v[170:173], v[92:95], a[64:79]
	v_accvgpr_read_b32 v99, a145
	v_cvt_pk_bf16_f32 v73, v88, v89
	v_cvt_pk_bf16_f32 v75, v90, v91
	v_fma_f32 v98, v98, s52, v52
	v_fma_f32 v99, v99, s52, v53
	v_pk_fma_f32 v[96:97], v[96:97], s[52:53], v[52:53] op_sel_hi:[1,0,1]
	v_pk_fma_f32 v[70:71], v[70:71], s[52:53], v[52:53] op_sel_hi:[1,0,1]
	v_exp_f32_e32 v104, v98
	s_waitcnt lgkmcnt(8)
	v_mfma_f32_32x32x16_bf16 a[96:111], v[174:177], v[92:95], a[96:111]
	v_accvgpr_read_b32 v95, a149
	v_accvgpr_read_b32 v94, a148
	v_fma_f32 v94, v94, s52, v52
	v_fma_f32 v95, v95, s52, v53
	v_exp_f32_e32 v105, v99
	v_exp_f32_e32 v106, v96
	v_exp_f32_e32 v107, v97
	v_exp_f32_e32 v108, v94
	s_waitcnt lgkmcnt(6)
	v_mfma_f32_32x32x16_bf16 a[0:15], v[178:181], v[72:75], a[0:15]
	v_exp_f32_e32 v109, v95
	v_pk_add_f32 v[68:69], v[90:91], v[68:69]
	v_accvgpr_read_b32 v89, a159
	v_accvgpr_read_b32 v88, a158
	v_accvgpr_read_b32 v91, a157
	v_accvgpr_read_b32 v90, a156
	v_accvgpr_read_b32 v93, a155
	s_waitcnt lgkmcnt(2)
; DEV f32x16 mfma32(bf16x8 a, bf16x8 b, f32x16 c) { return __builtin_amdgcn_mfma_f32_32x32x16_bf16(a, b, c, 0, 0, 0); }
; template <bool SAMPLE>
; DEV void attn_unit(CParams& p, int layer, int unit, float lam, float lam_init, char* lds, const int swave) {
;     ...
;       if (!SAMPLE || t + 1 < ntiles) gloadV(tn);
; #pragma unroll
;       for (int sl = 0; sl < 4; ++sl) {
; #pragma unroll
;         for (int e = 0; e < 4; ++e) {
;           const bf16x8 vf = tr8(Vs, AV_B, sl * 16, e * 32, lane);
;           O1[e] = mfma32(vf, pf[0][sl], O1[e]);
;         }
;         pf[1][sl] = sm8(sl < 2 ? S0 : S1, (sl & 1) * 8, nmc[1], ls[1]);
;       }
; #pragma unroll
;       for (int sl = 0; sl < 4; ++sl)
; #pragma unroll
;         for (int e = 0; e < 4; ++e) {
;           const bf16x8 vf = tr8(Vs, AV_B, sl * 16, e * 32, lane);
;           O2[e] = mfma32(vf, pf[1][sl], O2[e]);
;         }
;     }
;     if (t >= my_tiles && (!SAMPLE || t + 1 < ntiles)) gloadV(tn);
;     if (!SAMPLE || t + 1 < ntiles) lwrite((t + 1) & 1);
;     __syncthreads();
	v_mfma_f32_32x32x16_bf16 a[32:47], v[182:185], v[72:75], a[32:47]
	v_accvgpr_read_b32 v92, a154
	v_accvgpr_read_b32 v95, a153
	v_accvgpr_read_b32 v94, a152
	v_fma_f32 v94, v94, s52, v52
	v_fma_f32 v95, v95, s52, v53
	v_pk_fma_f32 v[92:93], v[92:93], s[52:53], v[52:53] op_sel_hi:[1,0,1]
	v_pk_fma_f32 v[90:91], v[90:91], s[52:53], v[52:53] op_sel_hi:[1,0,1]
	v_exp_f32_e32 v120, v94
	s_waitcnt lgkmcnt(1)
	v_mfma_f32_32x32x16_bf16 a[64:79], v[186:189], v[72:75], a[64:79]
	v_exp_f32_e32 v121, v95
	v_accvgpr_read_b32 v133, a133
	v_accvgpr_read_b32 v132, a132
	v_accvgpr_read_b32 v139, a131
	v_accvgpr_read_b32 v138, a130
	v_pk_fma_f32 v[132:133], v[132:133], s[52:53], v[52:53] op_sel_hi:[1,0,1]
	v_accvgpr_read_b32 v115, a139
	s_waitcnt lgkmcnt(0)
	v_mfma_f32_32x32x16_bf16 a[96:111], v[190:193], v[72:75], a[96:111]
	v_exp_f32_e32 v74, v70
	v_exp_f32_e32 v75, v71
	v_cvt_pk_bf16_f32 v70, v104, v105
	v_cvt_pk_bf16_f32 v71, v106, v107
	v_cvt_pk_bf16_f32 v72, v108, v109
	v_cvt_pk_bf16_f32 v73, v74, v75
	v_pk_add_f32 v[104:105], v[104:105], 0 op_sel_hi:[1,0]
	v_exp_f32_e32 v132, v132
	v_mfma_f32_32x32x16_bf16 a[16:31], v[116:119], v[70:73], a[16:31]
	v_add_f32_e64 v104, v106, v104
	v_add_f32_e64 v105, v107, v105
	v_accvgpr_read_b32 v106, a128
	v_accvgpr_read_b32 v119, a135
	v_accvgpr_read_b32 v118, a134
	v_accvgpr_read_b32 v107, a129
	v_pk_add_f32 v[104:105], v[108:109], v[104:105]
	v_pk_fma_f32 v[106:107], v[106:107], s[52:53], v[52:53] op_sel_hi:[1,0,1]
	v_mfma_f32_32x32x16_bf16 a[48:63], v[100:103], v[70:73], a[48:63]
	v_cvt_pk_bf16_f32 v100, v120, v121
	v_fma_f32 v108, v138, s52, v52
	v_fma_f32 v109, v139, s52, v53
	v_exp_f32_e32 v106, v106
	v_exp_f32_e32 v107, v107
	v_exp_f32_e32 v108, v108
	v_exp_f32_e32 v109, v109
	v_exp_f32_e32 v133, v133
	v_mfma_f32_32x32x16_bf16 a[80:95], v[122:125], v[70:73], a[80:95]
	v_exp_f32_e32 v122, v92
	v_exp_f32_e32 v123, v93
	v_exp_f32_e32 v124, v90
	v_exp_f32_e32 v125, v91
	v_pk_add_f32 v[74:75], v[74:75], v[104:105]
	v_cvt_pk_bf16_f32 v101, v122, v123
	v_pk_add_f32 v[104:105], v[120:121], 0 op_sel_hi:[1,0]
	v_mfma_f32_32x32x16_bf16 a[112:127], v[142:145], v[70:73], a[112:127]
	v_fma_f32 v70, v88, s52, v52
	v_fma_f32 v71, v89, s52, v53
	v_cvt_pk_bf16_f32 v102, v124, v125
	v_exp_f32_e32 v126, v70
	v_exp_f32_e32 v127, v71
	v_pk_add_f32 v[104:105], v[122:123], v[104:105]
	v_cvt_pk_bf16_f32 v103, v126, v127
	v_accvgpr_read_b32 v117, a137
	v_accvgpr_read_b32 v116, a136
	v_mfma_f32_32x32x16_bf16 a[16:31], v[146:149], v[100:103], a[16:31]
	v_add_f32_e64 v104, v124, v104
	v_add_f32_e64 v105, v125, v105
	v_accvgpr_read_b32 v114, a138
	v_add_f32_e64 v120, v126, v104
	v_add_f32_e64 v121, v127, v105
	v_pk_add_f32 v[104:105], v[106:107], 0 op_sel_hi:[1,0]
	v_accvgpr_read_b32 v111, a143
	v_accvgpr_read_b32 v110, a142
	v_accvgpr_read_b32 v113, a141
	v_mfma_f32_32x32x16_bf16 a[48:63], v[150:153], v[100:103], a[48:63]
	v_accvgpr_read_b32 v112, a140
	v_add_f32_e64 v104, v108, v104
	v_add_f32_e64 v105, v109, v105
	v_fma_f32 v112, v112, s52, v52
	v_fma_f32 v113, v113, s52, v53
	v_pk_add_f32 v[104:105], v[132:133], v[104:105]
	v_exp_f32_e32 v112, v112
	v_exp_f32_e32 v113, v113
	v_mfma_f32_32x32x16_bf16 a[80:95], v[154:157], v[100:103], a[80:95]
	s_andn2_b32 s8, 1, s37
	s_mul_i32 s8, s8, 0x9400
	s_add_i32 s8, s8, 16
	s_waitcnt vmcnt(0)
	v_add3_u32 v54, s8, v77, v76
	ds_write_b128 v54, v[4:7]
	v_add3_u32 v55, s8, v78, v76
	ds_write_b128 v55, v[194:197] offset:17408
	v_mfma_f32_32x32x16_bf16 a[112:127], v[158:161], v[100:103], a[112:127]
	v_add3_u32 v56, s8, v79, v76
	ds_write_b128 v56, v[0:3]
	v_add3_u32 v57, s8, v80, v76
	ds_write_b128 v57, v[198:201] offset:17408
	v_fma_f32 v100, v118, s52, v52
	v_fma_f32 v101, v119, s52, v53
	v_cvt_pk_bf16_f32 v102, v132, v133
	v_exp_f32_e32 v118, v100
	v_exp_f32_e32 v119, v101
	v_cvt_pk_bf16_f32 v100, v106, v107
	v_cvt_pk_bf16_f32 v101, v108, v109
	v_pk_fma_f32 v[106:107], v[116:117], s[52:53], v[52:53] op_sel_hi:[1,0,1]
	v_cvt_pk_bf16_f32 v103, v118, v119
	v_exp_f32_e32 v106, v106
	v_exp_f32_e32 v107, v107
	v_mfma_f32_32x32x16_bf16 a[16:31], v[162:165], v[100:103], a[16:31]
	v_fma_f32 v108, v114, s52, v52
	v_fma_f32 v109, v115, s52, v53
	v_add_f32_e64 v114, v118, v104
	v_add_f32_e64 v115, v119, v105
	v_exp_f32_e32 v108, v108
	v_exp_f32_e32 v109, v109
	v_pk_add_f32 v[116:117], v[106:107], 0 op_sel_hi:[1,0]
	v_cvt_pk_bf16_f32 v104, v106, v107
	v_pk_add_f32 v[106:107], v[108:109], v[116:117]
	v_mfma_f32_32x32x16_bf16 a[48:63], v[166:169], v[100:103], a[48:63]
	v_cvt_pk_bf16_f32 v105, v108, v109
	v_mfma_f32_32x32x16_bf16 a[80:95], v[170:173], v[100:103], a[80:95]
	v_add3_u32 v58, s8, v81, v76
	ds_write_b128 v58, v[12:15]
	v_add3_u32 v59, s8, v82, v76
	ds_write_b128 v59, v[202:205] offset:17408
	v_mfma_f32_32x32x16_bf16 a[112:127], v[174:177], v[100:103], a[112:127]
	v_add3_u32 v60, s8, v83, v76
	ds_write_b128 v60, v[8:11]
	v_add3_u32 v61, s8, v84, v76
	ds_write_b128 v61, v[206:209] offset:17408
	v_fma_f32 v100, v110, s52, v52
	v_fma_f32 v101, v111, s52, v53
	v_add_f32_e64 v102, v112, v106
	v_add_f32_e64 v103, v113, v107
	v_exp_f32_e32 v100, v100
	v_exp_f32_e32 v101, v101
	v_cvt_pk_bf16_f32 v106, v112, v113
	v_cvt_pk_bf16_f32 v107, v100, v101
	s_nop 1
	v_mfma_f32_32x32x16_bf16 a[16:31], v[178:181], v[104:107], a[16:31]
	v_add_f32_e64 v100, v100, v102
	v_add_f32_e64 v101, v101, v103
	v_mov_b32_e32 v102, v62
	v_mov_b32_e32 v103, v74
	v_mov_b32_e32 v74, v63
	v_pk_add_f32 v[62:63], v[102:103], v[74:75]
	v_mov_b32_e32 v74, v64
	v_mov_b32_e32 v75, v120
	v_mfma_f32_32x32x16_bf16 a[48:63], v[182:185], v[104:107], a[48:63]
	v_mov_b32_e32 v120, v65
	v_add_f32_e64 v64, v74, v120
	v_add_f32_e64 v65, v75, v121
	v_mov_b32_e32 v74, v66
	v_mov_b32_e32 v75, v114
	v_mov_b32_e32 v114, v67
	v_pk_add_f32 v[62:63], v[130:131], v[62:63]
	v_pk_add_f32 v[66:67], v[74:75], v[114:115]
	v_mfma_f32_32x32x16_bf16 a[80:95], v[186:189], v[104:107], a[80:95]
	v_mov_b32_e32 v74, v68
	v_mov_b32_e32 v75, v100
	v_mov_b32_e32 v100, v69
	v_add_f32_e64 v62, v64, v62
	v_add_f32_e64 v63, v65, v63
	v_pk_add_f32 v[68:69], v[74:75], v[100:101]
	v_pk_add_f32 v[62:63], v[66:67], v[62:63]
	v_mfma_f32_32x32x16_bf16 a[112:127], v[190:193], v[104:107], a[112:127]
	v_add_f32_e64 v130, v68, v62
	v_add_f32_e64 v131, v69, v63
	s_branch .Lattn_tail
.LBB0_245:
	s_andn2_b32 s8, 1, s37
	s_mul_i32 s8, s8, 0x9400
	s_add_i32 s8, s8, 16
	s_waitcnt vmcnt(0)
	v_add3_u32 v54, s8, v77, v76
	ds_write_b128 v54, v[4:7]
	v_add3_u32 v55, s8, v78, v76
	ds_write_b128 v55, v[194:197] offset:17408
	v_add3_u32 v56, s8, v79, v76
	ds_write_b128 v56, v[0:3]
	v_add3_u32 v57, s8, v80, v76
	ds_write_b128 v57, v[198:201] offset:17408
	v_add3_u32 v58, s8, v81, v76
	ds_write_b128 v58, v[12:15]
	v_add3_u32 v59, s8, v82, v76
	ds_write_b128 v59, v[202:205] offset:17408
	v_add3_u32 v60, s8, v83, v76
	ds_write_b128 v60, v[8:11]
	v_add3_u32 v61, s8, v84, v76
	ds_write_b128 v61, v[206:209] offset:17408
.Lattn_tail:
	s_andn2_b64 vcc, exec, s[6:7]
	s_waitcnt lgkmcnt(0)
	s_barrier
	s_cbranch_vccz .LBB0_249
	s_mov_b32 s37, s36
	s_branch .LBB0_243

; #define MLOAD(S, kt) { _Pragma("unroll") for (int i = 0; i < 4; ++i) { ra[S][i] = *(const u32x4*)(abase + ((size_t)(32 * i) * lda + (kt) * 64) * 2 + aoff); rb[S][i] = *(const u32x4*)(bbase + ((size_t)(32 * i) * K + (kt) * 64) * 2 + boff); } }
; #define MWRITE(S, buf) { char* as_ = lds + (buf) * 2 * GM_T; char* bs_ = as_ + GM_T; _Pragma("unroll") for (int i = 0; i < 4; ++i) { *(u32x4*)(as_ + (lrow + 32 * i) * GS_B + lch * 16) = ra[S][i]; *(u32x4*)(bs_ + (lrow + 32 * i) * GS_B + lch * 16) = rb[S][i]; } }
; template <int EPI>
; DEV void gemm_mini(CParams& p, int layer, const bf16_t* __restrict__ A, int lda, const bf16_t* __restrict__ Bt, int K, int n0, char* lds, const int swave) {
;     ...
;   MLOAD(0, 0) MLOAD(1, 1) MLOAD(2, 2) MLOAD(3, 3) MWRITE(0, 0) __syncthreads();
; #pragma unroll 1
;   for (int kt = 0; kt < nk; kt += 4) { MSTEP(0, kt) MSTEP(1, kt + 1) MSTEP(2, kt + 2) MSTEP(3, kt + 3) }
.LBB0_1135:
	s_add_i32 s3, s3, 4
	s_cmp_lt_u32 s3, 12
	s_cselect_b64 s[60:61], -1, 0
	s_cmp_gt_u32 s3, 11
	s_cselect_b64 s[56:57], -1, 0
	s_and_b64 vcc, exec, s[56:57]
	v_lshl_add_u64 v[2:3], v[0:1], 0, s[96:97]
	v_add_co_u32_e32 v10, vcc, 0xfffd0000, v0
	s_nop 1
	v_addc_co_u32_e32 v11, vcc, -1, v1, vcc
	v_add_co_u32_e32 v14, vcc, 0xf5d90000, v2
	global_load_dwordx4 v[10:13], v[10:11], off offset:-384
	s_nop 0
	v_addc_co_u32_e32 v15, vcc, -1, v3, vcc
	v_add_co_u32_e32 v18, vcc, 0xfffe0000, v0
	global_load_dwordx4 v[14:17], v[14:15], off offset:-384
	s_nop 0
	v_addc_co_u32_e32 v19, vcc, -1, v1, vcc
	v_add_co_u32_e32 v26, vcc, 0xf5da0000, v2
	global_load_dwordx4 v[18:21], v[18:19], off offset:-384
	s_nop 0
	v_addc_co_u32_e32 v27, vcc, -1, v3, vcc
	v_add_co_u32_e32 v34, vcc, 0xffff0000, v0
	global_load_dwordx4 v[26:29], v[26:27], off offset:-384
	s_nop 0
	v_addc_co_u32_e32 v35, vcc, -1, v1, vcc
	v_add_co_u32_e32 v46, vcc, 0xf5db0000, v2
	global_load_dwordx4 v[34:37], v[34:35], off offset:-384
	s_nop 0
	v_addc_co_u32_e32 v47, vcc, -1, v3, vcc
	v_add_co_u32_e32 v84, vcc, 0xf5dc0000, v2
	global_load_dwordx4 v[46:49], v[46:47], off offset:-384
	s_nop 0
	global_load_dwordx4 v[62:65], v[0:1], off offset:-384
	v_addc_co_u32_e32 v85, vcc, -1, v3, vcc
	global_load_dwordx4 v[84:87], v[84:85], off offset:-384
.LBB0_1137:
	s_cmp_gt_u32 s3, 10
	ds_read_b128 v[204:207], v8
	ds_read_b128 v[208:211], v6 offset:18432
	ds_read_b128 v[212:215], v6 offset:23040
	ds_read_b128 v[216:219], v6 offset:27648
	ds_read_b128 v[220:223], v6 offset:32256
	ds_read_b128 v[224:227], v8 offset:32
	ds_read_b128 v[228:231], v6 offset:18464
	ds_read_b128 v[232:235], v6 offset:23072
	ds_read_b128 v[236:239], v6 offset:27680
	ds_read_b128 v[244:247], v6 offset:32288
	s_waitcnt lgkmcnt(5)
	v_mfma_f32_32x32x16_bf16 a[0:15], v[208:211], v[204:207], a[0:15]
	v_mfma_f32_32x32x16_bf16 a[16:31], v[212:215], v[204:207], a[16:31]
	v_mfma_f32_32x32x16_bf16 a[32:47], v[216:219], v[204:207], a[32:47]
	v_mfma_f32_32x32x16_bf16 a[48:63], v[220:223], v[204:207], a[48:63]
	ds_read_b128 v[204:207], v8 offset:64
	ds_read_b128 v[208:211], v6 offset:18496
	ds_read_b128 v[212:215], v6 offset:23104
	ds_read_b128 v[216:219], v6 offset:27712
	ds_read_b128 v[220:223], v6 offset:32320
	s_waitcnt lgkmcnt(5)
	v_mfma_f32_32x32x16_bf16 a[0:15], v[228:231], v[224:227], a[0:15]
	v_mfma_f32_32x32x16_bf16 a[16:31], v[232:235], v[224:227], a[16:31]
	v_mfma_f32_32x32x16_bf16 a[32:47], v[236:239], v[224:227], a[32:47]
	v_mfma_f32_32x32x16_bf16 a[48:63], v[244:247], v[224:227], a[48:63]
	ds_read_b128 v[224:227], v8 offset:96
	ds_read_b128 v[228:231], v6 offset:18528
	ds_read_b128 v[232:235], v6 offset:23136
	ds_read_b128 v[236:239], v6 offset:27744
	ds_read_b128 v[244:247], v6 offset:32352
	s_waitcnt lgkmcnt(5)
	v_mfma_f32_32x32x16_bf16 a[0:15], v[208:211], v[204:207], a[0:15]
	v_mfma_f32_32x32x16_bf16 a[16:31], v[212:215], v[204:207], a[16:31]
	v_mfma_f32_32x32x16_bf16 a[32:47], v[216:219], v[204:207], a[32:47]
	v_mfma_f32_32x32x16_bf16 a[48:63], v[220:223], v[204:207], a[48:63]
	s_waitcnt lgkmcnt(0)
	v_mfma_f32_32x32x16_bf16 a[0:15], v[228:231], v[224:227], a[0:15]
	v_mfma_f32_32x32x16_bf16 a[16:31], v[232:235], v[224:227], a[16:31]
	v_mfma_f32_32x32x16_bf16 a[32:47], v[236:239], v[224:227], a[32:47]
	v_mfma_f32_32x32x16_bf16 a[48:63], v[244:247], v[224:227], a[48:63]
	s_waitcnt vmcnt(24)
	ds_write_b128 v4, v[22:25] offset:36864
	ds_write_b128 v4, v[30:33] offset:55296
	ds_write_b128 v4, v[42:45] offset:41472
	ds_write_b128 v4, v[58:61] offset:59904
	ds_write_b128 v4, v[70:73] offset:46080
	ds_write_b128 v4, v[92:95] offset:64512
	ds_write_b128 v4, v[100:103] offset:50688
	ds_write_b128 v9, v[112:115] offset:55296
	s_waitcnt lgkmcnt(0)
	s_barrier
	v_add_co_u32_e32 v22, vcc, 0xfffd0000, v0
	s_nop 1
	v_addc_co_u32_e32 v23, vcc, -1, v1, vcc
	v_add_co_u32_e32 v30, vcc, 0xf5d90000, v2
	global_load_dwordx4 v[22:25], v[22:23], off offset:-256
	s_nop 0
	v_addc_co_u32_e32 v31, vcc, -1, v3, vcc
	v_add_co_u32_e32 v42, vcc, 0xfffe0000, v0
	global_load_dwordx4 v[30:33], v[30:31], off offset:-256
	s_nop 0
	v_addc_co_u32_e32 v43, vcc, -1, v1, vcc
	v_add_co_u32_e32 v58, vcc, 0xf5da0000, v2
	global_load_dwordx4 v[42:45], v[42:43], off offset:-256
	s_nop 0
	v_addc_co_u32_e32 v59, vcc, -1, v3, vcc
	v_add_co_u32_e32 v70, vcc, 0xffff0000, v0
	global_load_dwordx4 v[58:61], v[58:59], off offset:-256
	s_nop 0
	v_addc_co_u32_e32 v71, vcc, -1, v1, vcc
	v_add_co_u32_e32 v92, vcc, 0xf5db0000, v2
	global_load_dwordx4 v[70:73], v[70:71], off offset:-256
	s_nop 0
	v_addc_co_u32_e32 v93, vcc, -1, v3, vcc
	v_add_co_u32_e32 v112, vcc, 0xf5dc0000, v2
	global_load_dwordx4 v[92:95], v[92:93], off offset:-256
	s_nop 0
	global_load_dwordx4 v[100:103], v[0:1], off offset:-256
	v_addc_co_u32_e32 v113, vcc, -1, v3, vcc
	global_load_dwordx4 v[112:115], v[112:113], off offset:-256
; #define MLOAD(S, kt) { _Pragma("unroll") for (int i = 0; i < 4; ++i) { ra[S][i] = *(const u32x4*)(abase + ((size_t)(32 * i) * lda + (kt) * 64) * 2 + aoff); rb[S][i] = *(const u32x4*)(bbase + ((size_t)(32 * i) * K + (kt) * 64) * 2 + boff); } }
; #define MWRITE(S, buf) { char* as_ = lds + (buf) * 2 * GM_T; char* bs_ = as_ + GM_T; _Pragma("unroll") for (int i = 0; i < 4; ++i) { *(u32x4*)(as_ + (lrow + 32 * i) * GS_B + lch * 16) = ra[S][i]; *(u32x4*)(bs_ + (lrow + 32 * i) * GS_B + lch * 16) = rb[S][i]; } }
; template <int EPI>
; DEV void gemm_mini(CParams& p, int layer, const bf16_t* __restrict__ A, int lda, const bf16_t* __restrict__ Bt, int K, int n0, char* lds, const int swave) {
;     ...
;   MLOAD(0, 0) MLOAD(1, 1) MLOAD(2, 2) MLOAD(3, 3) MWRITE(0, 0) __syncthreads();
; #pragma unroll 1
;   for (int kt = 0; kt < nk; kt += 4) { MSTEP(0, kt) MSTEP(1, kt + 1) MSTEP(2, kt + 2) MSTEP(3, kt + 3) }
.LBB0_1139:
	s_cmp_gt_u32 s3, 9
	ds_read_b128 v[204:207], v8 offset:36864
	ds_read_b128 v[208:211], v6 offset:55296
	ds_read_b128 v[212:215], v6 offset:59904
	ds_read_b128 v[216:219], v6 offset:64512
	ds_read_b128 v[220:223], v7 offset:13824
	ds_read_b128 v[224:227], v8 offset:36896
	ds_read_b128 v[228:231], v6 offset:55328
	ds_read_b128 v[232:235], v6 offset:59936
	ds_read_b128 v[236:239], v6 offset:64544
	ds_read_b128 v[244:247], v7 offset:13856
	s_waitcnt lgkmcnt(5)
	v_mfma_f32_32x32x16_bf16 a[0:15], v[208:211], v[204:207], a[0:15]
	v_mfma_f32_32x32x16_bf16 a[16:31], v[212:215], v[204:207], a[16:31]
	v_mfma_f32_32x32x16_bf16 a[32:47], v[216:219], v[204:207], a[32:47]
	v_mfma_f32_32x32x16_bf16 a[48:63], v[220:223], v[204:207], a[48:63]
	ds_read_b128 v[204:207], v8 offset:36928
	ds_read_b128 v[208:211], v6 offset:55360
	ds_read_b128 v[212:215], v6 offset:59968
	ds_read_b128 v[216:219], v6 offset:64576
	ds_read_b128 v[220:223], v7 offset:13888
	s_waitcnt lgkmcnt(5)
	v_mfma_f32_32x32x16_bf16 a[0:15], v[228:231], v[224:227], a[0:15]
	v_mfma_f32_32x32x16_bf16 a[16:31], v[232:235], v[224:227], a[16:31]
	v_mfma_f32_32x32x16_bf16 a[32:47], v[236:239], v[224:227], a[32:47]
	v_mfma_f32_32x32x16_bf16 a[48:63], v[244:247], v[224:227], a[48:63]
	ds_read_b128 v[224:227], v8 offset:36960
	ds_read_b128 v[228:231], v6 offset:55392
	ds_read_b128 v[232:235], v6 offset:60000
	ds_read_b128 v[236:239], v6 offset:64608
	ds_read_b128 v[244:247], v7 offset:13920
	s_waitcnt lgkmcnt(5)
	v_mfma_f32_32x32x16_bf16 a[0:15], v[208:211], v[204:207], a[0:15]
	v_mfma_f32_32x32x16_bf16 a[16:31], v[212:215], v[204:207], a[16:31]
	v_mfma_f32_32x32x16_bf16 a[32:47], v[216:219], v[204:207], a[32:47]
	v_mfma_f32_32x32x16_bf16 a[48:63], v[220:223], v[204:207], a[48:63]
	s_waitcnt lgkmcnt(0)
	v_mfma_f32_32x32x16_bf16 a[0:15], v[228:231], v[224:227], a[0:15]
	v_mfma_f32_32x32x16_bf16 a[16:31], v[232:235], v[224:227], a[16:31]
	v_mfma_f32_32x32x16_bf16 a[32:47], v[236:239], v[224:227], a[32:47]
	v_mfma_f32_32x32x16_bf16 a[48:63], v[244:247], v[224:227], a[48:63]
	s_waitcnt vmcnt(24)
	ds_write_b128 v4, v[38:41]
	ds_write_b128 v4, v[50:53] offset:18432
	ds_write_b128 v4, v[66:69] offset:4608
	ds_write_b128 v4, v[80:83] offset:23040
	ds_write_b128 v4, v[96:99] offset:9216
	ds_write_b128 v4, v[108:111] offset:27648
	ds_write_b128 v4, v[120:123] offset:13824
	ds_write_b128 v4, v[124:127] offset:32256
	s_waitcnt lgkmcnt(0)
	s_barrier
	v_add_co_u32_e32 v38, vcc, 0xfffd0000, v0
	s_nop 1
	v_addc_co_u32_e32 v39, vcc, -1, v1, vcc
	v_add_co_u32_e32 v50, vcc, 0xf5d90000, v2
	global_load_dwordx4 v[38:41], v[38:39], off offset:-128
	s_nop 0
	v_addc_co_u32_e32 v51, vcc, -1, v3, vcc
	v_add_co_u32_e32 v66, vcc, 0xfffe0000, v0
	global_load_dwordx4 v[50:53], v[50:51], off offset:-128
	s_nop 0
	v_addc_co_u32_e32 v67, vcc, -1, v1, vcc
	v_add_co_u32_e32 v80, vcc, 0xf5da0000, v2
	global_load_dwordx4 v[66:69], v[66:67], off offset:-128
	s_nop 0
	v_addc_co_u32_e32 v81, vcc, -1, v3, vcc
	v_add_co_u32_e32 v96, vcc, 0xffff0000, v0
	global_load_dwordx4 v[80:83], v[80:81], off offset:-128
	s_nop 0
	v_addc_co_u32_e32 v97, vcc, -1, v1, vcc
	v_add_co_u32_e32 v108, vcc, 0xf5db0000, v2
	global_load_dwordx4 v[96:99], v[96:97], off offset:-128
	s_nop 0
	v_addc_co_u32_e32 v109, vcc, -1, v3, vcc
	v_add_co_u32_e32 v124, vcc, 0xf5dc0000, v2
	global_load_dwordx4 v[108:111], v[108:109], off offset:-128
	s_nop 0
	global_load_dwordx4 v[120:123], v[0:1], off offset:-128
	v_addc_co_u32_e32 v125, vcc, -1, v3, vcc
	global_load_dwordx4 v[124:127], v[124:125], off offset:-128
.LBB0_1141:
	s_cmp_gt_u32 s3, 8
	ds_read_b128 v[204:207], v8
	ds_read_b128 v[208:211], v6 offset:18432
	ds_read_b128 v[212:215], v6 offset:23040
	ds_read_b128 v[216:219], v6 offset:27648
	ds_read_b128 v[220:223], v6 offset:32256
	ds_read_b128 v[224:227], v8 offset:32
	ds_read_b128 v[228:231], v6 offset:18464
	ds_read_b128 v[232:235], v6 offset:23072
	ds_read_b128 v[236:239], v6 offset:27680
	ds_read_b128 v[244:247], v6 offset:32288
	s_waitcnt lgkmcnt(5)
	v_mfma_f32_32x32x16_bf16 a[0:15], v[208:211], v[204:207], a[0:15]
	v_mfma_f32_32x32x16_bf16 a[16:31], v[212:215], v[204:207], a[16:31]
	v_mfma_f32_32x32x16_bf16 a[32:47], v[216:219], v[204:207], a[32:47]
	v_mfma_f32_32x32x16_bf16 a[48:63], v[220:223], v[204:207], a[48:63]
	ds_read_b128 v[204:207], v8 offset:64
	ds_read_b128 v[208:211], v6 offset:18496
	ds_read_b128 v[212:215], v6 offset:23104
	ds_read_b128 v[216:219], v6 offset:27712
	ds_read_b128 v[220:223], v6 offset:32320
	s_waitcnt lgkmcnt(5)
	v_mfma_f32_32x32x16_bf16 a[0:15], v[228:231], v[224:227], a[0:15]
	v_mfma_f32_32x32x16_bf16 a[16:31], v[232:235], v[224:227], a[16:31]
	v_mfma_f32_32x32x16_bf16 a[32:47], v[236:239], v[224:227], a[32:47]
	v_mfma_f32_32x32x16_bf16 a[48:63], v[244:247], v[224:227], a[48:63]
	ds_read_b128 v[224:227], v8 offset:96
	ds_read_b128 v[228:231], v6 offset:18528
	ds_read_b128 v[232:235], v6 offset:23136
	ds_read_b128 v[236:239], v6 offset:27744
	ds_read_b128 v[244:247], v6 offset:32352
	s_waitcnt lgkmcnt(5)
	v_mfma_f32_32x32x16_bf16 a[0:15], v[208:211], v[204:207], a[0:15]
	v_mfma_f32_32x32x16_bf16 a[16:31], v[212:215], v[204:207], a[16:31]
	v_mfma_f32_32x32x16_bf16 a[32:47], v[216:219], v[204:207], a[32:47]
	v_mfma_f32_32x32x16_bf16 a[48:63], v[220:223], v[204:207], a[48:63]
	s_waitcnt lgkmcnt(0)
	v_mfma_f32_32x32x16_bf16 a[0:15], v[228:231], v[224:227], a[0:15]
	v_mfma_f32_32x32x16_bf16 a[16:31], v[232:235], v[224:227], a[16:31]
	v_mfma_f32_32x32x16_bf16 a[32:47], v[236:239], v[224:227], a[32:47]
	v_mfma_f32_32x32x16_bf16 a[48:63], v[244:247], v[224:227], a[48:63]
	s_waitcnt vmcnt(24)
	ds_write_b128 v4, v[54:57] offset:36864
	ds_write_b128 v4, v[76:79] offset:55296
	ds_write_b128 v4, v[88:91] offset:41472
	ds_write_b128 v4, v[104:107] offset:59904
	ds_write_b128 v4, v[116:119] offset:46080
	ds_write_b128 v4, v[128:131] offset:64512
	ds_write_b128 v4, v[132:135] offset:50688
	ds_write_b128 v9, v[136:139] offset:55296
	s_waitcnt lgkmcnt(0)
	s_barrier
	v_add_co_u32_e32 v54, vcc, 0xfffd0000, v0
	s_nop 1
	v_addc_co_u32_e32 v55, vcc, -1, v1, vcc
	v_add_co_u32_e32 v76, vcc, 0xf5d90000, v2
	global_load_dwordx4 v[54:57], v[54:55], off
	s_nop 0
	v_addc_co_u32_e32 v77, vcc, -1, v3, vcc
	v_add_co_u32_e32 v88, vcc, 0xfffe0000, v0
	global_load_dwordx4 v[76:79], v[76:77], off
	s_nop 0
	v_addc_co_u32_e32 v89, vcc, -1, v1, vcc
	v_add_co_u32_e32 v104, vcc, 0xf5da0000, v2
	global_load_dwordx4 v[88:91], v[88:89], off
	s_nop 0
	v_addc_co_u32_e32 v105, vcc, -1, v3, vcc
	v_add_co_u32_e32 v116, vcc, 0xffff0000, v0
	global_load_dwordx4 v[104:107], v[104:105], off
	s_nop 0
	v_addc_co_u32_e32 v117, vcc, -1, v1, vcc
	v_add_co_u32_e32 v128, vcc, 0xf5db0000, v2
	global_load_dwordx4 v[116:119], v[116:117], off
	s_nop 0
	v_addc_co_u32_e32 v129, vcc, -1, v3, vcc
	v_add_co_u32_e32 v2, vcc, 0xf5dc0000, v2
	global_load_dwordx4 v[128:131], v[128:129], off
	s_nop 0
	global_load_dwordx4 v[132:135], v[0:1], off
	v_addc_co_u32_e32 v3, vcc, -1, v3, vcc
	global_load_dwordx4 v[136:139], v[2:3], off
; DEV uint32_t pk2(float lo, float hi) { f32x2 v; v[0] = lo; v[1] = hi; bf16v2 b = __builtin_convertvector(v, bf16v2); return __builtin_bit_cast(uint32_t, b); }
; #define MLOAD(S, kt) { _Pragma("unroll") for (int i = 0; i < 4; ++i) { ra[S][i] = *(const u32x4*)(abase + ((size_t)(32 * i) * lda + (kt) * 64) * 2 + aoff); rb[S][i] = *(const u32x4*)(bbase + ((size_t)(32 * i) * K + (kt) * 64) * 2 + boff); } }
; #define MWRITE(S, buf) { char* as_ = lds + (buf) * 2 * GM_T; char* bs_ = as_ + GM_T; _Pragma("unroll") for (int i = 0; i < 4; ++i) { *(u32x4*)(as_ + (lrow + 32 * i) * GS_B + lch * 16) = ra[S][i]; *(u32x4*)(bs_ + (lrow + 32 * i) * GS_B + lch * 16) = rb[S][i]; } }
; template <int EPI>
; DEV void gemm_mini(CParams& p, int layer, const bf16_t* __restrict__ A, int lda, const bf16_t* __restrict__ Bt, int K, int n0, char* lds, const int swave) {
;     ...
;   MLOAD(0, 0) MLOAD(1, 1) MLOAD(2, 2) MLOAD(3, 3) MWRITE(0, 0) __syncthreads();
; #pragma unroll 1
;   for (int kt = 0; kt < nk; kt += 4) { MSTEP(0, kt) MSTEP(1, kt + 1) MSTEP(2, kt + 2) MSTEP(3, kt + 3) }
;     ...
;   const int mc = TP + w * 32 + lr;
;   if (EPI == EPI_IN) {
;     const float rs = rscale_of(ssq, mc);
;     if (n0 < PW) {
;       bf16_t* prow = (bf16_t*)(ws + W_PROJ) + (size_t)mc * PW;
;       float* fo = nullptr;
;       if (n0 >= C_K) { const int cc = n0 >= C_V ? 1 : 0; fo = p.out + (cc ? O_VS : O_KS) + ((size_t)layer * TS + (mc - TP)) * 512 - (cc ? C_V : C_K); }
; #pragma unroll
;       for (int j = 0; j < 4; ++j)
; #pragma unroll
;         for (int g = 0; g < 4; ++g) {
;           const int n = n0 + j * 32 + 8 * g + 4 * hh;
;           f32x4 v; v[0] = acc[j][4 * g] * rs; v[1] = acc[j][4 * g + 1] * rs; v[2] = acc[j][4 * g + 2] * rs; v[3] = acc[j][4 * g + 3] * rs;
;           u32x2 pk; pk[0] = pk2(v[0], v[1]); pk[1] = pk2(v[2], v[3]);
;           *(u32x2*)(prow + n) = pk;
;           if (n0 >= C_K) __builtin_nontemporal_store(v, (f32x4*)(fo + n));
;         }
;     } else if (n0 == PW) {
;       if (hh == 0) { f32x4 v; v[0] = acc[0][0] * rs; v[1] = acc[0][1] * rs; v[2] = acc[0][2] * rs; v[3] = acc[0][3] * rs; *(f32x4*)((float*)(ws + W_DTRAW) + (size_t)mc * 4) = v; }
.LBB0_1143:
	s_andn2_b64 vcc, exec, s[60:61]
	ds_read_b128 v[204:207], v8 offset:36864
	ds_read_b128 v[208:211], v6 offset:55296
	ds_read_b128 v[212:215], v6 offset:59904
	ds_read_b128 v[216:219], v6 offset:64512
	ds_read_b128 v[220:223], v7 offset:13824
	ds_read_b128 v[224:227], v8 offset:36896
	ds_read_b128 v[228:231], v6 offset:55328
	ds_read_b128 v[232:235], v6 offset:59936
	ds_read_b128 v[236:239], v6 offset:64544
	ds_read_b128 v[244:247], v7 offset:13856
	s_waitcnt lgkmcnt(5)
	v_mfma_f32_32x32x16_bf16 a[0:15], v[208:211], v[204:207], a[0:15]
	v_mfma_f32_32x32x16_bf16 a[16:31], v[212:215], v[204:207], a[16:31]
	v_mfma_f32_32x32x16_bf16 a[32:47], v[216:219], v[204:207], a[32:47]
	v_mfma_f32_32x32x16_bf16 a[48:63], v[220:223], v[204:207], a[48:63]
	ds_read_b128 v[204:207], v8 offset:36928
	ds_read_b128 v[208:211], v6 offset:55360
	ds_read_b128 v[212:215], v6 offset:59968
	ds_read_b128 v[216:219], v6 offset:64576
	ds_read_b128 v[220:223], v7 offset:13888
	s_waitcnt lgkmcnt(5)
	v_mfma_f32_32x32x16_bf16 a[0:15], v[228:231], v[224:227], a[0:15]
	v_mfma_f32_32x32x16_bf16 a[16:31], v[232:235], v[224:227], a[16:31]
	v_mfma_f32_32x32x16_bf16 a[32:47], v[236:239], v[224:227], a[32:47]
	v_mfma_f32_32x32x16_bf16 a[48:63], v[244:247], v[224:227], a[48:63]
	ds_read_b128 v[224:227], v8 offset:36960
	ds_read_b128 v[228:231], v6 offset:55392
	ds_read_b128 v[232:235], v6 offset:60000
	ds_read_b128 v[236:239], v6 offset:64608
	ds_read_b128 v[244:247], v7 offset:13920
	s_waitcnt lgkmcnt(5)
	v_mfma_f32_32x32x16_bf16 a[0:15], v[208:211], v[204:207], a[0:15]
	v_mfma_f32_32x32x16_bf16 a[16:31], v[212:215], v[204:207], a[16:31]
	v_mfma_f32_32x32x16_bf16 a[32:47], v[216:219], v[204:207], a[32:47]
	v_mfma_f32_32x32x16_bf16 a[48:63], v[220:223], v[204:207], a[48:63]
	s_waitcnt lgkmcnt(0)
	v_mfma_f32_32x32x16_bf16 a[0:15], v[228:231], v[224:227], a[0:15]
	v_mfma_f32_32x32x16_bf16 a[16:31], v[232:235], v[224:227], a[16:31]
	v_mfma_f32_32x32x16_bf16 a[32:47], v[236:239], v[224:227], a[32:47]
	v_mfma_f32_32x32x16_bf16 a[48:63], v[244:247], v[224:227], a[48:63]
	s_cbranch_vccnz .LBB0_1134
	s_waitcnt vmcnt(24)
	ds_write_b128 v4, v[10:13]
	ds_write_b128 v4, v[14:17] offset:18432
	ds_write_b128 v4, v[18:21] offset:4608
	ds_write_b128 v4, v[26:29] offset:23040
	ds_write_b128 v4, v[34:37] offset:9216
	ds_write_b128 v4, v[46:49] offset:27648
	ds_write_b128 v4, v[62:65] offset:13824
	ds_write_b128 v4, v[84:87] offset:32256
	s_branch .LBB0_1134
.LBB0_1145:
	s_waitcnt vmcnt(0)
	v_or_b32_e32 v240, s19, v5
	v_lshlrev_b64 v[0:1], 5, v[240:241]
	v_lshl_add_u64 v[4:5], s[8:9], 0, v[0:1]
	global_load_dwordx4 v[0:3], v[4:5], off
	s_nop 0
	global_load_dwordx4 v[4:7], v[4:5], off offset:16
	s_cmp_lg_u32 s31, 24
	s_mov_b64 s[56:57], -1
	s_waitcnt vmcnt(1)
	v_mov_b32_e32 v8, v1
	v_mov_b32_e32 v9, v2
	v_mov_b32_e32 v1, v3
	s_waitcnt vmcnt(0)
	v_mov_b32_e32 v2, v6
	v_mov_b32_e32 v3, v4
	v_mov_b32_e32 v4, v7
	v_pk_add_f32 v[0:1], v[8:9], v[0:1]
	v_pk_add_f32 v[2:3], v[2:3], v[4:5]
	v_add_f32_e32 v0, v0, v1
	v_add_f32_e32 v0, v0, v3
	v_add_f32_e32 v0, v2, v0
	v_fmamk_f32 v0, v0, 0x3a800000, v242
	v_mul_f32_e32 v1, 0x4b800000, v0
	v_cmp_gt_f32_e32 vcc, s25, v0
	s_nop 1
	v_cndmask_b32_e32 v0, v0, v1, vcc
	v_rsq_f32_e32 v64, v0
	v_accvgpr_read_b32 v0, a0
	v_accvgpr_read_b32 v1, a1
	v_accvgpr_read_b32 v2, a2
	v_mul_f32_e32 v65, 0x45800000, v64
	v_accvgpr_read_b32 v3, a3
	v_accvgpr_read_b32 v4, a4
	v_accvgpr_read_b32 v5, a5
	v_accvgpr_read_b32 v6, a6
	v_accvgpr_read_b32 v7, a7
	v_accvgpr_read_b32 v8, a8
	v_accvgpr_read_b32 v9, a9
	v_accvgpr_read_b32 v10, a10
	v_accvgpr_read_b32 v11, a11
	v_accvgpr_read_b32 v12, a12
	v_accvgpr_read_b32 v13, a13
	v_accvgpr_read_b32 v14, a14
	v_accvgpr_read_b32 v15, a15
	v_cndmask_b32_e32 v68, v64, v65, vcc
	s_cbranch_scc0 .LBB0_1181
	v_accvgpr_read_b32 v16, a48
	v_accvgpr_read_b32 v32, a32
	v_accvgpr_read_b32 v63, a31
	s_cmp_gt_i32 s31, 15
	v_accvgpr_read_b32 v17, a49
	v_accvgpr_read_b32 v18, a50
	v_accvgpr_read_b32 v19, a51
	v_accvgpr_read_b32 v20, a52
	v_accvgpr_read_b32 v21, a53
	v_accvgpr_read_b32 v22, a54
	v_accvgpr_read_b32 v23, a55
	v_accvgpr_read_b32 v24, a56
	v_accvgpr_read_b32 v25, a57
	v_accvgpr_read_b32 v26, a58
	v_accvgpr_read_b32 v27, a59
	v_accvgpr_read_b32 v28, a60
	v_accvgpr_read_b32 v29, a61
	v_accvgpr_read_b32 v30, a62
	v_accvgpr_read_b32 v31, a63
	v_accvgpr_read_b32 v33, a33
	v_accvgpr_read_b32 v34, a34
	v_accvgpr_read_b32 v35, a35
	v_accvgpr_read_b32 v36, a36
	v_accvgpr_read_b32 v37, a37
	v_accvgpr_read_b32 v38, a38
	v_accvgpr_read_b32 v39, a39
	v_accvgpr_read_b32 v40, a40
	v_accvgpr_read_b32 v41, a41
	v_accvgpr_read_b32 v42, a42
	v_accvgpr_read_b32 v43, a43
	v_accvgpr_read_b32 v44, a44
	v_accvgpr_read_b32 v45, a45
	v_accvgpr_read_b32 v46, a46
	v_accvgpr_read_b32 v47, a47
	v_accvgpr_read_b32 v62, a30
	v_accvgpr_read_b32 v61, a29
	v_accvgpr_read_b32 v60, a28
	v_accvgpr_read_b32 v59, a27
	v_accvgpr_read_b32 v58, a26
	v_accvgpr_read_b32 v57, a25
	v_accvgpr_read_b32 v56, a24
	v_accvgpr_read_b32 v55, a23
	v_accvgpr_read_b32 v54, a22
	v_accvgpr_read_b32 v53, a21
	v_accvgpr_read_b32 v52, a20
	v_accvgpr_read_b32 v51, a19
	v_accvgpr_read_b32 v50, a18
	v_accvgpr_read_b32 v49, a17
	v_accvgpr_read_b32 v48, a16
	s_cselect_b64 s[56:57], -1, 0
	s_cmp_lt_i32 s31, 16
	v_mov_b64_e32 v[70:71], 0
	s_cbranch_scc1 .LBB0_1148
	s_cmpk_gt_u32 s2, 0x9ff
	s_cselect_b32 s3, s34, 0x2819a000
	v_add_u32_e32 v64, 0xffff8000, v240
	v_mov_b32_e32 v65, v241
	s_cselect_b32 s40, s38, 0xffffe000
	s_add_u32 s36, s28, s3
	s_addc_u32 s37, s29, 0
	v_lshlrev_b64 v[64:65], 11, v[64:65]
	v_lshl_add_u64 v[64:65], s[36:37], 0, v[64:65]
	v_lshl_add_u64 v[70:71], v[64:65], 0, s[40:41]
